# v7 + each load segment ends with s_setprio 1 then ONE s_waitcnt vmcnt(8) lgkmcnt(0) before the barrier (was two waits then setprio)
# speedup vs baseline: 1.0304x; 1.0025x over previous
; #define PG8_STAGE(bufoff, gbase, voff) do { _Pragma("unroll") for (int _i = 0; _i < 2; ++_i) \
;         __builtin_amdgcn_global_load_lds((const unsigned*)((const char*)(gbase) + (voff)[_i]), (LAS unsigned*)(lds + (bufoff) + ldsw + _i * 8192), 16, 0, 0); } while (0)
; #define PG8_LDA(dst, b, h) do { _Pragma("unroll") for (int m = 0; m < 4; ++m) _Pragma("unroll") for (int k = 0; k < 2; ++k) dst[m][k] = *(const LAS bf16x8*)(lds + PG8_SA(b, h) + aoff + m * 2048 + k * KOFF); } while (0)
; #define PG8_LDB(dst, b, h) do { _Pragma("unroll") for (int n = 0; n < 2; ++n) _Pragma("unroll") for (int k = 0; k < 2; ++k) dst[n][k] = *(const LAS bf16x8*)(lds + PG8_SB(b, h) + boff + n * 2048 + k * KOFF); } while (0)
; #define PG8_WAIT_V(n) asm volatile("s_waitcnt vmcnt(" #n ")" ::: "memory")
; #define PG8_WAIT_L(n) asm volatile("s_waitcnt lgkmcnt(" #n ")" ::: "memory")
; #define PG8_BAR __builtin_amdgcn_s_barrier()
; #define PG8_SCHED __builtin_amdgcn_sched_barrier(0)
; template <class Epi, bool ALIGN_EPI = true, bool FP8 = false>
; __device__ __forceinline__ void gemm_phase(LAS unsigned char* lds, const Gemm g, const StaticOrder& S, const Epi& E, const int wid) {
;     ...
;             const char* a1 = cA + (size_t)(t + 1) * kstep;
;             const char* a2 = last ? nA : cA + (size_t)(t + 2) * kstep; const char* b2 = last ? nB : cB + (size_t)(t + 2) * kstep;
;             const char* a3 = a2 + kstep; const char* b3 = b2 + kstep;
;             PG8_LDB(B0, 0, 0); PG8_LDB(B1, 0, 1); PG8_SCHED; PG8_LDA(At, 0, 0); PG8_STAGE(PG8_SA(1, 1), a1 + hstep, voffA);
;             PG8_WAIT_V(8); PG8_WAIT_L(0); PG8_BAR; PG8_MMA(0, 0, At, B0); PG8_MMA(0, 1, At, B1); PG8_BAR; PG8_SCHED;
;             PG8_LDA(At, 0, 1); PG8_STAGE(PG8_SB(0, 0), b2, voffB); PG8_STAGE(PG8_SB(0, 1), b2 + hstep, voffB); PG8_STAGE(PG8_SA(0, 0), a2, voffA);
.LBB0_506:
	ds_read_b128 v[146:149], v137
	ds_read_b128 v[154:157], v137 offset:1024
	ds_read_b128 v[158:161], v137 offset:2048
	ds_read_b128 v[162:165], v137 offset:3072
	ds_read_b128 v[166:169], v152
	ds_read_b128 v[170:173], v152 offset:1024
	ds_read_b128 v[174:177], v152 offset:2048
	ds_read_b128 v[178:181], v152 offset:3072
	s_add_i32 s52, s34, 2
	s_add_u32 s35, s30, 0xfff80080
	s_addc_u32 s36, s31, -1
	s_cmp_eq_u32 s39, s34
	s_cselect_b32 s34, s38, s42
	s_cselect_b32 s37, s3, s36
	s_cselect_b32 s36, s23, s35
	s_cselect_b32 s35, s25, s43
	v_lshl_add_u64 v[214:215], s[30:31], 0, v[140:141]
	s_add_i32 m0, s75, 0xc000
	ds_read_b128 v[182:185], v153
	ds_read_b128 v[186:189], v153 offset:1024
	ds_read_b128 v[190:193], v153 offset:2048
	ds_read_b128 v[194:197], v153 offset:3072
	ds_read_b128 v[198:201], v153 offset:4096
	ds_read_b128 v[202:205], v153 offset:5120
	ds_read_b128 v[206:209], v153 offset:6144
	ds_read_b128 v[210:213], v153 offset:7168
	global_load_lds_dwordx4 v[214:215], off
	v_lshl_add_u64 v[214:215], s[30:31], 0, v[142:143]
	s_add_i32 m0, s75, 0xe000
	s_nop 0
	global_load_lds_dwordx4 v[214:215], off
	s_setprio 1
	s_waitcnt vmcnt(8) lgkmcnt(0)
	s_barrier
	v_mfma_f32_16x16x32_bf16 v[124:127], v[146:149], v[182:185], v[124:127]
	v_mfma_f32_16x16x32_bf16 v[120:123], v[158:161], v[182:185], v[120:123]
	v_mfma_f32_16x16x32_bf16 v[108:111], v[146:149], v[190:193], v[108:111]
	v_mfma_f32_16x16x32_bf16 v[104:107], v[158:161], v[190:193], v[104:107]
	v_mfma_f32_16x16x32_bf16 v[92:95], v[146:149], v[198:201], v[92:95]
	v_mfma_f32_16x16x32_bf16 v[88:91], v[158:161], v[198:201], v[88:91]
	v_mfma_f32_16x16x32_bf16 v[76:79], v[146:149], v[206:209], v[76:79]
	v_mfma_f32_16x16x32_bf16 v[72:75], v[158:161], v[206:209], v[72:75]
	v_mfma_f32_16x16x32_bf16 v[124:127], v[154:157], v[186:189], v[124:127]
	v_mfma_f32_16x16x32_bf16 v[120:123], v[162:165], v[186:189], v[120:123]
	v_mfma_f32_16x16x32_bf16 v[108:111], v[154:157], v[194:197], v[108:111]
	v_mfma_f32_16x16x32_bf16 v[104:107], v[162:165], v[194:197], v[104:107]
	v_mfma_f32_16x16x32_bf16 v[92:95], v[154:157], v[202:205], v[92:95]
	v_mfma_f32_16x16x32_bf16 v[88:91], v[162:165], v[202:205], v[88:91]
	v_mfma_f32_16x16x32_bf16 v[76:79], v[154:157], v[210:213], v[76:79]
	v_mfma_f32_16x16x32_bf16 v[72:75], v[162:165], v[210:213], v[72:75]
	v_mfma_f32_16x16x32_bf16 v[116:119], v[166:169], v[182:185], v[116:119]
	v_mfma_f32_16x16x32_bf16 v[112:115], v[174:177], v[182:185], v[112:115]
	v_mfma_f32_16x16x32_bf16 v[100:103], v[166:169], v[190:193], v[100:103]
	v_mfma_f32_16x16x32_bf16 v[96:99], v[174:177], v[190:193], v[96:99]
	v_mfma_f32_16x16x32_bf16 v[84:87], v[166:169], v[198:201], v[84:87]
	v_mfma_f32_16x16x32_bf16 v[80:83], v[174:177], v[198:201], v[80:83]
	v_mfma_f32_16x16x32_bf16 v[68:71], v[166:169], v[206:209], v[68:71]
	v_mfma_f32_16x16x32_bf16 v[64:67], v[174:177], v[206:209], v[64:67]
	v_mfma_f32_16x16x32_bf16 v[116:119], v[170:173], v[186:189], v[116:119]
	v_mfma_f32_16x16x32_bf16 v[112:115], v[178:181], v[186:189], v[112:115]
	v_mfma_f32_16x16x32_bf16 v[100:103], v[170:173], v[194:197], v[100:103]
	v_mfma_f32_16x16x32_bf16 v[96:99], v[178:181], v[194:197], v[96:99]
	v_mfma_f32_16x16x32_bf16 v[84:87], v[170:173], v[202:205], v[84:87]
	v_mfma_f32_16x16x32_bf16 v[80:83], v[178:181], v[202:205], v[80:83]
	v_mfma_f32_16x16x32_bf16 v[68:71], v[170:173], v[210:213], v[68:71]
	v_mfma_f32_16x16x32_bf16 v[64:67], v[178:181], v[210:213], v[64:67]
	s_barrier
	s_setprio 0
	s_add_i32 s54, s86, s48
	v_lshl_add_u64 v[214:215], s[34:35], 0, v[132:133]
	s_mov_b32 m0, s54
	ds_read_b128 v[182:185], v153 offset:16384
	ds_read_b128 v[186:189], v153 offset:17408
	ds_read_b128 v[190:193], v153 offset:18432
	ds_read_b128 v[194:197], v153 offset:19456
	ds_read_b128 v[198:201], v153 offset:20480
	ds_read_b128 v[202:205], v153 offset:21504
	ds_read_b128 v[206:209], v153 offset:22528
	ds_read_b128 v[210:213], v153 offset:23552
	global_load_lds_dwordx4 v[214:215], off
	s_add_i32 m0, s54, 0x2000
	s_add_u32 s64, s34, 0x80000
	v_lshl_add_u64 v[216:217], s[34:35], 0, v[128:129]
	s_addc_u32 s65, s35, 0
	s_add_i32 s54, s87, s48
	global_load_lds_dwordx4 v[216:217], off
	v_lshl_add_u64 v[218:219], s[64:65], 0, v[132:133]
	s_mov_b32 m0, s54
	v_lshl_add_u64 v[220:221], s[36:37], 0, v[130:131]
	global_load_lds_dwordx4 v[218:219], off
	v_lshl_add_u64 v[218:219], s[64:65], 0, v[128:129]
	s_add_i32 m0, s54, 0x2000
	s_nop 0
	global_load_lds_dwordx4 v[218:219], off
	v_lshl_add_u64 v[218:219], s[36:37], 0, v[134:135]
	s_mov_b32 m0, s75
	s_nop 0
	global_load_lds_dwordx4 v[218:219], off
	s_mov_b32 m0, s76
	s_nop 0
	global_load_lds_dwordx4 v[220:221], off
	s_setprio 1
	s_waitcnt vmcnt(8) lgkmcnt(0)
	s_barrier
; #define PG8_STAGE(bufoff, gbase, voff) do { _Pragma("unroll") for (int _i = 0; _i < 2; ++_i) \
;         __builtin_amdgcn_global_load_lds((const unsigned*)((const char*)(gbase) + (voff)[_i]), (LAS unsigned*)(lds + (bufoff) + ldsw + _i * 8192), 16, 0, 0); } while (0)
; #define PG8_LDA(dst, b, h) do { _Pragma("unroll") for (int m = 0; m < 4; ++m) _Pragma("unroll") for (int k = 0; k < 2; ++k) dst[m][k] = *(const LAS bf16x8*)(lds + PG8_SA(b, h) + aoff + m * 2048 + k * KOFF); } while (0)
; #define PG8_LDB(dst, b, h) do { _Pragma("unroll") for (int n = 0; n < 2; ++n) _Pragma("unroll") for (int k = 0; k < 2; ++k) dst[n][k] = *(const LAS bf16x8*)(lds + PG8_SB(b, h) + boff + n * 2048 + k * KOFF); } while (0)
; #define PG8_WAIT_V(n) asm volatile("s_waitcnt vmcnt(" #n ")" ::: "memory")
; #define PG8_WAIT_L(n) asm volatile("s_waitcnt lgkmcnt(" #n ")" ::: "memory")
; #define PG8_BAR __builtin_amdgcn_s_barrier()
; #define PG8_SCHED __builtin_amdgcn_sched_barrier(0)
; template <class Epi, bool ALIGN_EPI = true, bool FP8 = false>
; __device__ __forceinline__ void gemm_phase(LAS unsigned char* lds, const Gemm g, const StaticOrder& S, const Epi& E, const int wid) {
;     ...
;             PG8_WAIT_V(8); PG8_WAIT_L(0); PG8_BAR; PG8_MMA(1, 0, At, B0); PG8_MMA(1, 1, At, B1); PG8_BAR; PG8_SCHED;
;             PG8_LDB(B0, 1, 0); PG8_LDB(B1, 1, 1); PG8_SCHED; PG8_LDA(At, 1, 0); PG8_STAGE(PG8_SA(0, 1), a2 + hstep, voffA);
;             PG8_WAIT_V(8); PG8_WAIT_L(0); PG8_BAR; PG8_MMA(0, 0, At, B0); PG8_MMA(0, 1, At, B1); PG8_BAR; PG8_SCHED;
	v_mfma_f32_16x16x32_bf16 v[60:63], v[146:149], v[182:185], v[60:63]
	v_mfma_f32_16x16x32_bf16 v[56:59], v[158:161], v[182:185], v[56:59]
	v_mfma_f32_16x16x32_bf16 v[44:47], v[146:149], v[190:193], v[44:47]
	v_mfma_f32_16x16x32_bf16 v[40:43], v[158:161], v[190:193], v[40:43]
	v_mfma_f32_16x16x32_bf16 v[28:31], v[146:149], v[198:201], v[28:31]
	v_mfma_f32_16x16x32_bf16 v[24:27], v[158:161], v[198:201], v[24:27]
	v_mfma_f32_16x16x32_bf16 v[12:15], v[146:149], v[206:209], v[12:15]
	v_mfma_f32_16x16x32_bf16 v[8:11], v[158:161], v[206:209], v[8:11]
	v_mfma_f32_16x16x32_bf16 v[60:63], v[154:157], v[186:189], v[60:63]
	v_mfma_f32_16x16x32_bf16 v[56:59], v[162:165], v[186:189], v[56:59]
	v_mfma_f32_16x16x32_bf16 v[44:47], v[154:157], v[194:197], v[44:47]
	v_mfma_f32_16x16x32_bf16 v[40:43], v[162:165], v[194:197], v[40:43]
	v_mfma_f32_16x16x32_bf16 v[28:31], v[154:157], v[202:205], v[28:31]
	v_mfma_f32_16x16x32_bf16 v[24:27], v[162:165], v[202:205], v[24:27]
	v_mfma_f32_16x16x32_bf16 v[12:15], v[154:157], v[210:213], v[12:15]
	v_mfma_f32_16x16x32_bf16 v[8:11], v[162:165], v[210:213], v[8:11]
	v_mfma_f32_16x16x32_bf16 v[52:55], v[166:169], v[182:185], v[52:55]
	v_mfma_f32_16x16x32_bf16 v[48:51], v[174:177], v[182:185], v[48:51]
	v_mfma_f32_16x16x32_bf16 v[36:39], v[166:169], v[190:193], v[36:39]
	v_mfma_f32_16x16x32_bf16 v[32:35], v[174:177], v[190:193], v[32:35]
	v_mfma_f32_16x16x32_bf16 v[20:23], v[166:169], v[198:201], v[20:23]
	v_mfma_f32_16x16x32_bf16 v[16:19], v[174:177], v[198:201], v[16:19]
	v_mfma_f32_16x16x32_bf16 v[4:7], v[166:169], v[206:209], v[4:7]
	v_mfma_f32_16x16x32_bf16 v[0:3], v[174:177], v[206:209], v[0:3]
	v_mfma_f32_16x16x32_bf16 v[52:55], v[170:173], v[186:189], v[52:55]
	v_mfma_f32_16x16x32_bf16 v[48:51], v[178:181], v[186:189], v[48:51]
	v_mfma_f32_16x16x32_bf16 v[36:39], v[170:173], v[194:197], v[36:39]
	v_mfma_f32_16x16x32_bf16 v[32:35], v[178:181], v[194:197], v[32:35]
	v_mfma_f32_16x16x32_bf16 v[20:23], v[170:173], v[202:205], v[20:23]
	v_mfma_f32_16x16x32_bf16 v[16:19], v[178:181], v[202:205], v[16:19]
	v_mfma_f32_16x16x32_bf16 v[4:7], v[170:173], v[210:213], v[4:7]
	v_mfma_f32_16x16x32_bf16 v[0:3], v[178:181], v[210:213], v[0:3]
	s_barrier
	s_setprio 0
	s_add_i32 s54, 0, 0x18000
	s_add_i32 s64, 0, 0x1c000
	v_add_u32_e32 v162, s54, v150
	v_add_u32_e32 v178, s64, v150
	ds_read_b128 v[146:149], v162
	ds_read_b128 v[154:157], v162 offset:1024
	ds_read_b128 v[158:161], v162 offset:2048
	ds_read_b128 v[162:165], v162 offset:3072
	ds_read_b128 v[166:169], v178
	ds_read_b128 v[170:173], v178 offset:1024
	ds_read_b128 v[174:177], v178 offset:2048
	ds_read_b128 v[178:181], v178 offset:3072
	s_add_u32 s36, s36, 0x80000
	s_addc_u32 s37, s37, 0
	s_mov_b32 m0, s77
	v_lshl_add_u64 v[222:223], s[36:37], 0, v[134:135]
	ds_read_b128 v[182:185], v153 offset:32768
	ds_read_b128 v[186:189], v153 offset:33792
	ds_read_b128 v[190:193], v153 offset:34816
	ds_read_b128 v[194:197], v153 offset:35840
	ds_read_b128 v[198:201], v153 offset:36864
	ds_read_b128 v[202:205], v153 offset:37888
	ds_read_b128 v[206:209], v153 offset:38912
	ds_read_b128 v[210:213], v153 offset:39936
	global_load_lds_dwordx4 v[222:223], off
	v_lshl_add_u64 v[222:223], s[36:37], 0, v[130:131]
	s_mov_b32 m0, s78
	s_nop 0
	global_load_lds_dwordx4 v[222:223], off
	s_setprio 1
	s_waitcnt vmcnt(8) lgkmcnt(0)
	s_barrier
	v_mfma_f32_16x16x32_bf16 v[124:127], v[146:149], v[182:185], v[124:127]
	v_mfma_f32_16x16x32_bf16 v[120:123], v[158:161], v[182:185], v[120:123]
	v_mfma_f32_16x16x32_bf16 v[108:111], v[146:149], v[190:193], v[108:111]
	v_mfma_f32_16x16x32_bf16 v[104:107], v[158:161], v[190:193], v[104:107]
	v_mfma_f32_16x16x32_bf16 v[92:95], v[146:149], v[198:201], v[92:95]
	v_mfma_f32_16x16x32_bf16 v[88:91], v[158:161], v[198:201], v[88:91]
	v_mfma_f32_16x16x32_bf16 v[76:79], v[146:149], v[206:209], v[76:79]
	v_mfma_f32_16x16x32_bf16 v[72:75], v[158:161], v[206:209], v[72:75]
	v_mfma_f32_16x16x32_bf16 v[124:127], v[154:157], v[186:189], v[124:127]
	v_mfma_f32_16x16x32_bf16 v[120:123], v[162:165], v[186:189], v[120:123]
	v_mfma_f32_16x16x32_bf16 v[108:111], v[154:157], v[194:197], v[108:111]
	v_mfma_f32_16x16x32_bf16 v[104:107], v[162:165], v[194:197], v[104:107]
	v_mfma_f32_16x16x32_bf16 v[92:95], v[154:157], v[202:205], v[92:95]
	v_mfma_f32_16x16x32_bf16 v[88:91], v[162:165], v[202:205], v[88:91]
	v_mfma_f32_16x16x32_bf16 v[76:79], v[154:157], v[210:213], v[76:79]
	v_mfma_f32_16x16x32_bf16 v[72:75], v[162:165], v[210:213], v[72:75]
	v_mfma_f32_16x16x32_bf16 v[116:119], v[166:169], v[182:185], v[116:119]
	v_mfma_f32_16x16x32_bf16 v[112:115], v[174:177], v[182:185], v[112:115]
	v_mfma_f32_16x16x32_bf16 v[100:103], v[166:169], v[190:193], v[100:103]
	v_mfma_f32_16x16x32_bf16 v[96:99], v[174:177], v[190:193], v[96:99]
	v_mfma_f32_16x16x32_bf16 v[84:87], v[166:169], v[198:201], v[84:87]
	v_mfma_f32_16x16x32_bf16 v[80:83], v[174:177], v[198:201], v[80:83]
	v_mfma_f32_16x16x32_bf16 v[68:71], v[166:169], v[206:209], v[68:71]
	v_mfma_f32_16x16x32_bf16 v[64:67], v[174:177], v[206:209], v[64:67]
	v_mfma_f32_16x16x32_bf16 v[116:119], v[170:173], v[186:189], v[116:119]
	v_mfma_f32_16x16x32_bf16 v[112:115], v[178:181], v[186:189], v[112:115]
	v_mfma_f32_16x16x32_bf16 v[100:103], v[170:173], v[194:197], v[100:103]
	v_mfma_f32_16x16x32_bf16 v[96:99], v[178:181], v[194:197], v[96:99]
	v_mfma_f32_16x16x32_bf16 v[84:87], v[170:173], v[202:205], v[84:87]
	v_mfma_f32_16x16x32_bf16 v[80:83], v[178:181], v[202:205], v[80:83]
	v_mfma_f32_16x16x32_bf16 v[68:71], v[170:173], v[210:213], v[68:71]
	v_mfma_f32_16x16x32_bf16 v[64:67], v[178:181], v[210:213], v[64:67]
	s_barrier
; #define PG8_STAGE(bufoff, gbase, voff) do { _Pragma("unroll") for (int _i = 0; _i < 2; ++_i) \
;         __builtin_amdgcn_global_load_lds((const unsigned*)((const char*)(gbase) + (voff)[_i]), (LAS unsigned*)(lds + (bufoff) + ldsw + _i * 8192), 16, 0, 0); } while (0)
; #define PG8_LDA(dst, b, h) do { _Pragma("unroll") for (int m = 0; m < 4; ++m) _Pragma("unroll") for (int k = 0; k < 2; ++k) dst[m][k] = *(const LAS bf16x8*)(lds + PG8_SA(b, h) + aoff + m * 2048 + k * KOFF); } while (0)
; #define PG8_WAIT_V(n) asm volatile("s_waitcnt vmcnt(" #n ")" ::: "memory")
; #define PG8_WAIT_L(n) asm volatile("s_waitcnt lgkmcnt(" #n ")" ::: "memory")
; #define PG8_BAR __builtin_amdgcn_s_barrier()
; #define PG8_SCHED __builtin_amdgcn_sched_barrier(0)
; template <class Epi, bool ALIGN_EPI = true, bool FP8 = false>
; __device__ __forceinline__ void gemm_phase(LAS unsigned char* lds, const Gemm g, const StaticOrder& S, const Epi& E, const int wid) {
;     ...
;             PG8_LDA(At, 1, 1); PG8_STAGE(PG8_SB(1, 0), b3, voffB); PG8_STAGE(PG8_SB(1, 1), b3 + hstep, voffB); PG8_STAGE(PG8_SA(1, 0), a3, voffA);
;             PG8_WAIT_V(8); PG8_WAIT_L(0); PG8_BAR; PG8_MMA(1, 0, At, B0); PG8_MMA(1, 1, At, B1); PG8_BAR; PG8_SCHED;
;         }
;         if constexpr (ALIGN_EPI) { if (wr == 0) PG8_BAR; }
	s_setprio 0
	s_add_i32 s36, s54, s48
	v_lshl_add_u64 v[214:215], v[214:215], 0, s[16:17]
	s_mov_b32 m0, s36
	ds_read_b128 v[182:185], v153 offset:49152
	ds_read_b128 v[186:189], v153 offset:50176
	ds_read_b128 v[190:193], v153 offset:51200
	ds_read_b128 v[194:197], v153 offset:52224
	ds_read_b128 v[198:201], v153 offset:53248
	ds_read_b128 v[202:205], v153 offset:54272
	ds_read_b128 v[206:209], v153 offset:55296
	ds_read_b128 v[210:213], v153 offset:56320
	global_load_lds_dwordx4 v[214:215], off
	s_add_i32 m0, s36, 0x2000
	s_add_u32 s34, s34, 0x80080
	v_lshl_add_u64 v[214:215], v[216:217], 0, s[16:17]
	s_addc_u32 s35, s35, 0
	s_add_i32 s36, s64, s48
	global_load_lds_dwordx4 v[214:215], off
	v_lshl_add_u64 v[214:215], s[34:35], 0, v[132:133]
	s_mov_b32 m0, s36
	s_nop 0
	global_load_lds_dwordx4 v[214:215], off
	v_lshl_add_u64 v[214:215], s[34:35], 0, v[128:129]
	s_add_i32 m0, s36, 0x2000
	s_nop 0
	global_load_lds_dwordx4 v[214:215], off
	v_lshl_add_u64 v[214:215], v[218:219], 0, s[16:17]
	s_mov_b32 m0, s83
	s_nop 0
	global_load_lds_dwordx4 v[214:215], off
	v_lshl_add_u64 v[214:215], v[220:221], 0, s[16:17]
	s_mov_b32 m0, s84
	s_nop 0
	global_load_lds_dwordx4 v[214:215], off
	s_setprio 1
	s_waitcnt vmcnt(8) lgkmcnt(0)
	s_barrier
	v_mfma_f32_16x16x32_bf16 v[60:63], v[146:149], v[182:185], v[60:63]
	v_mfma_f32_16x16x32_bf16 v[56:59], v[158:161], v[182:185], v[56:59]
	v_mfma_f32_16x16x32_bf16 v[44:47], v[146:149], v[190:193], v[44:47]
	v_mfma_f32_16x16x32_bf16 v[40:43], v[158:161], v[190:193], v[40:43]
	v_mfma_f32_16x16x32_bf16 v[28:31], v[146:149], v[198:201], v[28:31]
	v_mfma_f32_16x16x32_bf16 v[24:27], v[158:161], v[198:201], v[24:27]
	v_mfma_f32_16x16x32_bf16 v[12:15], v[146:149], v[206:209], v[12:15]
	v_mfma_f32_16x16x32_bf16 v[8:11], v[158:161], v[206:209], v[8:11]
	v_mfma_f32_16x16x32_bf16 v[60:63], v[154:157], v[186:189], v[60:63]
	v_mfma_f32_16x16x32_bf16 v[56:59], v[162:165], v[186:189], v[56:59]
	v_mfma_f32_16x16x32_bf16 v[44:47], v[154:157], v[194:197], v[44:47]
	v_mfma_f32_16x16x32_bf16 v[40:43], v[162:165], v[194:197], v[40:43]
	v_mfma_f32_16x16x32_bf16 v[28:31], v[154:157], v[202:205], v[28:31]
	v_mfma_f32_16x16x32_bf16 v[24:27], v[162:165], v[202:205], v[24:27]
	v_mfma_f32_16x16x32_bf16 v[12:15], v[154:157], v[210:213], v[12:15]
	v_mfma_f32_16x16x32_bf16 v[8:11], v[162:165], v[210:213], v[8:11]
	v_mfma_f32_16x16x32_bf16 v[52:55], v[166:169], v[182:185], v[52:55]
	v_mfma_f32_16x16x32_bf16 v[48:51], v[174:177], v[182:185], v[48:51]
	v_mfma_f32_16x16x32_bf16 v[36:39], v[166:169], v[190:193], v[36:39]
	v_mfma_f32_16x16x32_bf16 v[32:35], v[174:177], v[190:193], v[32:35]
	v_mfma_f32_16x16x32_bf16 v[20:23], v[166:169], v[198:201], v[20:23]
	v_mfma_f32_16x16x32_bf16 v[16:19], v[174:177], v[198:201], v[16:19]
	v_mfma_f32_16x16x32_bf16 v[4:7], v[166:169], v[206:209], v[4:7]
	v_mfma_f32_16x16x32_bf16 v[0:3], v[174:177], v[206:209], v[0:3]
	v_mfma_f32_16x16x32_bf16 v[52:55], v[170:173], v[186:189], v[52:55]
	v_mfma_f32_16x16x32_bf16 v[48:51], v[178:181], v[186:189], v[48:51]
	v_mfma_f32_16x16x32_bf16 v[36:39], v[170:173], v[194:197], v[36:39]
	v_mfma_f32_16x16x32_bf16 v[32:35], v[178:181], v[194:197], v[32:35]
	v_mfma_f32_16x16x32_bf16 v[20:23], v[170:173], v[202:205], v[20:23]
	v_mfma_f32_16x16x32_bf16 v[16:19], v[178:181], v[202:205], v[16:19]
	v_mfma_f32_16x16x32_bf16 v[4:7], v[170:173], v[210:213], v[4:7]
	v_mfma_f32_16x16x32_bf16 v[0:3], v[178:181], v[210:213], v[0:3]
	s_barrier
	s_setprio 0
	s_add_u32 s30, s30, 0x100
	s_addc_u32 s31, s31, 0
	s_add_u32 s42, s42, 0x100
	s_addc_u32 s43, s43, 0
	s_cmp_ge_u32 s52, s9
	s_mov_b32 s34, s52
	s_cbranch_scc0 .LBB0_506
	s_and_b64 vcc, exec, s[12:13]
	s_cbranch_vccz .LBB0_509

; #define PG8_STAGE(bufoff, gbase, voff) do { _Pragma("unroll") for (int _i = 0; _i < 2; ++_i) \
;         __builtin_amdgcn_global_load_lds((const unsigned*)((const char*)(gbase) + (voff)[_i]), (LAS unsigned*)(lds + (bufoff) + ldsw + _i * 8192), 16, 0, 0); } while (0)
; #define PG8_LDA(dst, b, h) do { _Pragma("unroll") for (int m = 0; m < 4; ++m) _Pragma("unroll") for (int k = 0; k < 2; ++k) dst[m][k] = *(const LAS bf16x8*)(lds + PG8_SA(b, h) + aoff + m * 2048 + k * KOFF); } while (0)
; #define PG8_LDB(dst, b, h) do { _Pragma("unroll") for (int n = 0; n < 2; ++n) _Pragma("unroll") for (int k = 0; k < 2; ++k) dst[n][k] = *(const LAS bf16x8*)(lds + PG8_SB(b, h) + boff + n * 2048 + k * KOFF); } while (0)
; #define PG8_WAIT_V(n) asm volatile("s_waitcnt vmcnt(" #n ")" ::: "memory")
; #define PG8_WAIT_L(n) asm volatile("s_waitcnt lgkmcnt(" #n ")" ::: "memory")
; #define PG8_BAR __builtin_amdgcn_s_barrier()
; #define PG8_SCHED __builtin_amdgcn_sched_barrier(0)
; template <class Epi, bool ALIGN_EPI = true, bool FP8 = false>
; __device__ __forceinline__ void gemm_phase(LAS unsigned char* lds, const Gemm g, const StaticOrder& S, const Epi& E, const int wid) {
;     ...
;             const char* a1 = cA + (size_t)(t + 1) * kstep;
;             const char* a2 = last ? nA : cA + (size_t)(t + 2) * kstep; const char* b2 = last ? nB : cB + (size_t)(t + 2) * kstep;
;             const char* a3 = a2 + kstep; const char* b3 = b2 + kstep;
;             PG8_LDB(B0, 0, 0); PG8_LDB(B1, 0, 1); PG8_SCHED; PG8_LDA(At, 0, 0); PG8_STAGE(PG8_SA(1, 1), a1 + hstep, voffA);
;             PG8_WAIT_V(8); PG8_WAIT_L(0); PG8_BAR; PG8_MMA(0, 0, At, B0); PG8_MMA(0, 1, At, B1); PG8_BAR; PG8_SCHED;
;             PG8_LDA(At, 0, 1); PG8_STAGE(PG8_SB(0, 0), b2, voffB); PG8_STAGE(PG8_SB(0, 1), b2 + hstep, voffB); PG8_STAGE(PG8_SA(0, 0), a2, voffA);
;             PG8_WAIT_V(8); PG8_WAIT_L(0); PG8_BAR; PG8_MMA(1, 0, At, B0); PG8_MMA(1, 1, At, B1); PG8_BAR; PG8_SCHED;
;             PG8_LDB(B0, 1, 0); PG8_LDB(B1, 1, 1); PG8_SCHED; PG8_LDA(At, 1, 0); PG8_STAGE(PG8_SA(0, 1), a2 + hstep, voffA);
;             PG8_WAIT_V(8); PG8_WAIT_L(0); PG8_BAR; PG8_MMA(0, 0, At, B0); PG8_MMA(0, 1, At, B1); PG8_BAR; PG8_SCHED;
.LBB0_572:
	ds_read_b128 v[152:155], v190
	ds_read_b128 v[156:159], v190 offset:1024
	ds_read_b128 v[144:147], v190 offset:2048
	ds_read_b128 v[148:151], v190 offset:3072
	ds_read_b128 v[136:139], v191
	ds_read_b128 v[140:143], v191 offset:1024
	ds_read_b128 v[128:131], v191 offset:2048
	ds_read_b128 v[132:135], v191 offset:3072
	s_add_i32 s3, s34, 2
	s_add_u32 s35, s30, 0xfffc0080
	s_addc_u32 s36, s31, -1
	s_cmp_eq_u32 s86, s34
	s_cselect_b32 s34, s85, s87
	s_cselect_b32 s37, s21, s36
	s_cselect_b32 s36, s23, s35
	s_cselect_b32 s35, s84, s88
	v_lshl_add_u64 v[220:221], s[30:31], 0, v[170:171]
	s_add_i32 m0, s27, 0xc000
	ds_read_b128 v[178:181], v192
	ds_read_b128 v[182:185], v192 offset:1024
	ds_read_b128 v[196:199], v192 offset:2048
	ds_read_b128 v[200:203], v192 offset:3072
	ds_read_b128 v[204:207], v192 offset:4096
	ds_read_b128 v[208:211], v192 offset:5120
	ds_read_b128 v[212:215], v192 offset:6144
	ds_read_b128 v[216:219], v192 offset:7168
	global_load_lds_dwordx4 v[220:221], off
	v_lshl_add_u64 v[220:221], s[30:31], 0, v[172:173]
	s_add_i32 m0, s27, 0xe000
	s_nop 0
	global_load_lds_dwordx4 v[220:221], off
	s_setprio 1
	s_waitcnt vmcnt(8) lgkmcnt(0)
	s_barrier
	v_mfma_f32_16x16x128_f8f6f4 v[120:123], v[152:159], v[178:185], v[120:123]
	v_mfma_f32_16x16x128_f8f6f4 v[124:127], v[144:151], v[178:185], v[124:127]
	v_mfma_f32_16x16x128_f8f6f4 v[112:115], v[152:159], v[196:203], v[112:115]
	v_mfma_f32_16x16x128_f8f6f4 v[116:119], v[144:151], v[196:203], v[116:119]
	v_mfma_f32_16x16x128_f8f6f4 v[104:107], v[152:159], v[204:211], v[104:107]
	v_mfma_f32_16x16x128_f8f6f4 v[108:111], v[144:151], v[204:211], v[108:111]
	v_mfma_f32_16x16x128_f8f6f4 v[88:91], v[152:159], v[212:219], v[88:91]
	v_mfma_f32_16x16x128_f8f6f4 v[92:95], v[144:151], v[212:219], v[92:95]
	v_mfma_f32_16x16x128_f8f6f4 v[96:99], v[136:143], v[178:185], v[96:99]
	v_mfma_f32_16x16x128_f8f6f4 v[100:103], v[128:135], v[178:185], v[100:103]
	v_mfma_f32_16x16x128_f8f6f4 v[80:83], v[136:143], v[196:203], v[80:83]
	v_mfma_f32_16x16x128_f8f6f4 v[84:87], v[128:135], v[196:203], v[84:87]
	v_mfma_f32_16x16x128_f8f6f4 v[72:75], v[136:143], v[204:211], v[72:75]
	v_mfma_f32_16x16x128_f8f6f4 v[76:79], v[128:135], v[204:211], v[76:79]
	v_mfma_f32_16x16x128_f8f6f4 v[64:67], v[136:143], v[212:219], v[64:67]
	v_mfma_f32_16x16x128_f8f6f4 v[68:71], v[128:135], v[212:219], v[68:71]
	s_barrier
	s_setprio 0
	s_add_i32 s42, s75, s48
	v_lshl_add_u64 v[178:179], s[34:35], 0, v[164:165]
	s_mov_b32 m0, s42
	ds_read_b128 v[196:199], v192 offset:16384
	ds_read_b128 v[200:203], v192 offset:17408
	ds_read_b128 v[204:207], v192 offset:18432
	ds_read_b128 v[208:211], v192 offset:19456
	ds_read_b128 v[212:215], v192 offset:20480
	ds_read_b128 v[216:219], v192 offset:21504
	ds_read_b128 v[220:223], v192 offset:22528
	ds_read_b128 v[224:227], v192 offset:23552
	global_load_lds_dwordx4 v[178:179], off
	s_add_i32 m0, s42, 0x2000
	s_add_u32 s42, s34, 0x40000
	v_lshl_add_u64 v[180:181], s[34:35], 0, v[160:161]
	s_addc_u32 s43, s35, 0
	s_add_i32 s52, s76, s48
	global_load_lds_dwordx4 v[180:181], off
	v_lshl_add_u64 v[182:183], s[42:43], 0, v[164:165]
	s_mov_b32 m0, s52
	v_lshl_add_u64 v[184:185], s[36:37], 0, v[162:163]
	global_load_lds_dwordx4 v[182:183], off
	v_lshl_add_u64 v[182:183], s[42:43], 0, v[160:161]
	s_add_i32 m0, s52, 0x2000
	s_nop 0
	global_load_lds_dwordx4 v[182:183], off
	v_lshl_add_u64 v[182:183], s[36:37], 0, v[166:167]
	s_mov_b32 m0, s27
	s_nop 0
	global_load_lds_dwordx4 v[182:183], off
	s_mov_b32 m0, s55
	s_nop 0
	global_load_lds_dwordx4 v[184:185], off
	s_setprio 1
	s_waitcnt vmcnt(8) lgkmcnt(0)
	s_barrier
	v_mfma_f32_16x16x128_f8f6f4 v[56:59], v[152:159], v[196:203], v[56:59]
	v_mfma_f32_16x16x128_f8f6f4 v[60:63], v[144:151], v[196:203], v[60:63]
	v_mfma_f32_16x16x128_f8f6f4 v[48:51], v[152:159], v[204:211], v[48:51]
	v_mfma_f32_16x16x128_f8f6f4 v[52:55], v[144:151], v[204:211], v[52:55]
	v_mfma_f32_16x16x128_f8f6f4 v[40:43], v[152:159], v[212:219], v[40:43]
	v_mfma_f32_16x16x128_f8f6f4 v[44:47], v[144:151], v[212:219], v[44:47]
	v_mfma_f32_16x16x128_f8f6f4 v[228:231], v[152:159], v[220:227], v[24:27]
	v_mfma_f32_16x16x128_f8f6f4 v[232:235], v[144:151], v[220:227], v[28:31]
	v_mfma_f32_16x16x128_f8f6f4 v[236:239], v[136:143], v[196:203], v[32:35]
	v_mfma_f32_16x16x128_f8f6f4 v[240:243], v[128:135], v[196:203], v[36:39]
	v_mfma_f32_16x16x128_f8f6f4 v[244:247], v[136:143], v[204:211], v[16:19]
	v_mfma_f32_16x16x128_f8f6f4 v[204:207], v[128:135], v[204:211], v[20:23]
	v_mfma_f32_16x16x128_f8f6f4 v[208:211], v[136:143], v[212:219], v[8:11]
	v_mfma_f32_16x16x128_f8f6f4 v[212:215], v[128:135], v[212:219], v[12:15]
	v_mfma_f32_16x16x128_f8f6f4 v[216:219], v[136:143], v[220:227], v[0:3]
	v_mfma_f32_16x16x128_f8f6f4 v[220:223], v[128:135], v[220:227], v[4:7]
	s_barrier
	s_setprio 0
	s_add_i32 s42, 0, 0x18000
	s_add_i32 s43, 0, 0x1c000
	s_nop 0
	v_add_u32_e32 v12, s42, v187
	v_add_u32_e32 v16, s43, v187
	ds_read_b128 v[0:3], v12
	ds_read_b128 v[4:7], v12 offset:1024
	ds_read_b128 v[8:11], v12 offset:2048
	ds_read_b128 v[12:15], v12 offset:3072
	ds_read_b128 v[128:131], v16
	ds_read_b128 v[132:135], v16 offset:1024
	ds_read_b128 v[136:139], v16 offset:2048
	ds_read_b128 v[140:143], v16 offset:3072
	s_add_u32 s36, s36, 0x40000
	s_addc_u32 s37, s37, 0
	s_mov_b32 m0, s64
	v_lshl_add_u64 v[152:153], s[36:37], 0, v[166:167]
	ds_read_b128 v[16:19], v192 offset:32768
	ds_read_b128 v[20:23], v192 offset:33792
	ds_read_b128 v[24:27], v192 offset:34816
	ds_read_b128 v[28:31], v192 offset:35840
	ds_read_b128 v[32:35], v192 offset:36864
	ds_read_b128 v[36:39], v192 offset:37888
	ds_read_b128 v[144:147], v192 offset:38912
	ds_read_b128 v[148:151], v192 offset:39936
	global_load_lds_dwordx4 v[152:153], off
	v_lshl_add_u64 v[152:153], s[36:37], 0, v[162:163]
	s_mov_b32 m0, s65
	s_nop 0
	global_load_lds_dwordx4 v[152:153], off
	s_setprio 1
	s_waitcnt vmcnt(8) lgkmcnt(0)
	s_barrier
; #define PG8_STAGE(bufoff, gbase, voff) do { _Pragma("unroll") for (int _i = 0; _i < 2; ++_i) \
;         __builtin_amdgcn_global_load_lds((const unsigned*)((const char*)(gbase) + (voff)[_i]), (LAS unsigned*)(lds + (bufoff) + ldsw + _i * 8192), 16, 0, 0); } while (0)
; #define PG8_LDA(dst, b, h) do { _Pragma("unroll") for (int m = 0; m < 4; ++m) _Pragma("unroll") for (int k = 0; k < 2; ++k) dst[m][k] = *(const LAS bf16x8*)(lds + PG8_SA(b, h) + aoff + m * 2048 + k * KOFF); } while (0)
; #define PG8_WAIT_V(n) asm volatile("s_waitcnt vmcnt(" #n ")" ::: "memory")
; #define PG8_WAIT_L(n) asm volatile("s_waitcnt lgkmcnt(" #n ")" ::: "memory")
; #define PG8_BAR __builtin_amdgcn_s_barrier()
; #define PG8_SCHED __builtin_amdgcn_sched_barrier(0)
; template <class Epi, bool ALIGN_EPI = true, bool FP8 = false>
; __device__ __forceinline__ void gemm_phase(LAS unsigned char* lds, const Gemm g, const StaticOrder& S, const Epi& E, const int wid) {
;     ...
;             PG8_WAIT_V(8); PG8_WAIT_L(0); PG8_BAR; PG8_MMA(0, 0, At, B0); PG8_MMA(0, 1, At, B1); PG8_BAR; PG8_SCHED;
;             PG8_LDA(At, 1, 1); PG8_STAGE(PG8_SB(1, 0), b3, voffB); PG8_STAGE(PG8_SB(1, 1), b3 + hstep, voffB); PG8_STAGE(PG8_SA(1, 0), a3, voffA);
;             PG8_WAIT_V(8); PG8_WAIT_L(0); PG8_BAR; PG8_MMA(1, 0, At, B0); PG8_MMA(1, 1, At, B1); PG8_BAR; PG8_SCHED;
;         }
	v_mfma_f32_16x16x128_f8f6f4 v[120:123], v[0:7], v[16:23], v[120:123]
	v_mfma_f32_16x16x128_f8f6f4 v[124:127], v[8:15], v[16:23], v[124:127]
	v_mfma_f32_16x16x128_f8f6f4 v[112:115], v[0:7], v[24:31], v[112:115]
	v_mfma_f32_16x16x128_f8f6f4 v[116:119], v[8:15], v[24:31], v[116:119]
	v_mfma_f32_16x16x128_f8f6f4 v[104:107], v[0:7], v[32:39], v[104:107]
	v_mfma_f32_16x16x128_f8f6f4 v[108:111], v[8:15], v[32:39], v[108:111]
	v_mfma_f32_16x16x128_f8f6f4 v[88:91], v[0:7], v[144:151], v[88:91]
	v_mfma_f32_16x16x128_f8f6f4 v[92:95], v[8:15], v[144:151], v[92:95]
	v_mfma_f32_16x16x128_f8f6f4 v[96:99], v[128:135], v[16:23], v[96:99]
	v_mfma_f32_16x16x128_f8f6f4 v[100:103], v[136:143], v[16:23], v[100:103]
	v_mfma_f32_16x16x128_f8f6f4 v[80:83], v[128:135], v[24:31], v[80:83]
	v_mfma_f32_16x16x128_f8f6f4 v[84:87], v[136:143], v[24:31], v[84:87]
	v_mfma_f32_16x16x128_f8f6f4 v[72:75], v[128:135], v[32:39], v[72:75]
	v_mfma_f32_16x16x128_f8f6f4 v[76:79], v[136:143], v[32:39], v[76:79]
	v_mfma_f32_16x16x128_f8f6f4 v[64:67], v[128:135], v[144:151], v[64:67]
	v_mfma_f32_16x16x128_f8f6f4 v[68:71], v[136:143], v[144:151], v[68:71]
	s_barrier
	s_setprio 0
	s_add_i32 s36, s42, s48
	v_lshl_add_u64 v[24:25], v[178:179], 0, s[8:9]
	s_mov_b32 m0, s36
	ds_read_b128 v[16:19], v192 offset:49152
	ds_read_b128 v[20:23], v192 offset:50176
	ds_read_b128 v[144:147], v192 offset:51200
	ds_read_b128 v[148:151], v192 offset:52224
	ds_read_b128 v[152:155], v192 offset:53248
	ds_read_b128 v[156:159], v192 offset:54272
	ds_read_b128 v[196:199], v192 offset:55296
	ds_read_b128 v[200:203], v192 offset:56320
	global_load_lds_dwordx4 v[24:25], off
	s_add_i32 m0, s36, 0x2000
	s_add_u32 s34, s34, 0x40080
	v_lshl_add_u64 v[24:25], v[180:181], 0, s[8:9]
	s_addc_u32 s35, s35, 0
	s_add_i32 s36, s43, s48
	global_load_lds_dwordx4 v[24:25], off
	v_lshl_add_u64 v[24:25], s[34:35], 0, v[164:165]
	s_mov_b32 m0, s36
	s_nop 0
	global_load_lds_dwordx4 v[24:25], off
	v_lshl_add_u64 v[24:25], s[34:35], 0, v[160:161]
	s_add_i32 m0, s36, 0x2000
	s_nop 0
	global_load_lds_dwordx4 v[24:25], off
	v_lshl_add_u64 v[24:25], v[182:183], 0, s[8:9]
	s_mov_b32 m0, s70
	s_nop 0
	global_load_lds_dwordx4 v[24:25], off
	v_lshl_add_u64 v[24:25], v[184:185], 0, s[8:9]
	s_mov_b32 m0, s71
	s_nop 0
	global_load_lds_dwordx4 v[24:25], off
	s_setprio 1
	s_waitcnt vmcnt(8) lgkmcnt(0)
	s_barrier
	v_mfma_f32_16x16x128_f8f6f4 v[56:59], v[0:7], v[16:23], v[56:59]
	v_mfma_f32_16x16x128_f8f6f4 v[60:63], v[8:15], v[16:23], v[60:63]
	v_mfma_f32_16x16x128_f8f6f4 v[48:51], v[0:7], v[144:151], v[48:51]
	v_mfma_f32_16x16x128_f8f6f4 v[52:55], v[8:15], v[144:151], v[52:55]
	v_mfma_f32_16x16x128_f8f6f4 v[40:43], v[0:7], v[152:159], v[40:43]
	v_mfma_f32_16x16x128_f8f6f4 v[44:47], v[8:15], v[152:159], v[44:47]
	v_mfma_f32_16x16x128_f8f6f4 v[24:27], v[0:7], v[196:203], v[228:231]
	v_mfma_f32_16x16x128_f8f6f4 v[28:31], v[8:15], v[196:203], v[232:235]
	v_mfma_f32_16x16x128_f8f6f4 v[32:35], v[128:135], v[16:23], v[236:239]
	v_mfma_f32_16x16x128_f8f6f4 v[36:39], v[136:143], v[16:23], v[240:243]
	v_mfma_f32_16x16x128_f8f6f4 v[16:19], v[128:135], v[144:151], v[244:247]
	v_mfma_f32_16x16x128_f8f6f4 v[20:23], v[136:143], v[144:151], v[204:207]
	v_mfma_f32_16x16x128_f8f6f4 v[8:11], v[128:135], v[152:159], v[208:211]
	v_mfma_f32_16x16x128_f8f6f4 v[12:15], v[136:143], v[152:159], v[212:215]
	v_mfma_f32_16x16x128_f8f6f4 v[0:3], v[128:135], v[196:203], v[216:219]
	v_mfma_f32_16x16x128_f8f6f4 v[4:7], v[136:143], v[196:203], v[220:223]
	s_barrier
	s_setprio 0
	s_add_u32 s30, s30, 0x100
	s_addc_u32 s31, s31, 0
	s_add_u32 s87, s87, 0x100
	s_addc_u32 s88, s88, 0
	s_cmp_ge_u32 s3, s83
	s_mov_b32 s34, s3
	s_cbranch_scc0 .LBB0_572
;     __device__ __forceinline__ void operator()(const Acc& acc, const Unit& u, int wr, int wc, int fr, int fq) const {
;     ...
;                         const f32x4 v0 = acc[ai][bj][m][0] * QS, v1 = acc[ai][bj][m][1] * QS;
;     ...
;                         const f32x4 v0 = acc[ai][bj][m][0] * QS, v1 = acc[ai][bj][m][1] * QS;
	v_pk_mul_f32 v[122:123], v[122:123], s[14:15] op_sel_hi:[1,0]
	v_pk_mul_f32 v[128:129], v[120:121], s[14:15] op_sel_hi:[1,0]
	v_pk_mul_f32 v[120:121], v[126:127], s[14:15] op_sel_hi:[1,0]
	v_pk_mul_f32 v[124:125], v[124:125], s[14:15] op_sel_hi:[1,0]
	v_pk_mul_f32 v[132:133], v[98:99], s[14:15] op_sel_hi:[1,0]
	v_pk_mul_f32 v[136:137], v[96:97], s[14:15] op_sel_hi:[1,0]
	v_pk_mul_f32 v[130:131], v[102:103], s[14:15] op_sel_hi:[1,0]
	v_pk_mul_f32 v[134:135], v[100:101], s[14:15] op_sel_hi:[1,0]
	v_pk_mul_f32 v[100:101], v[114:115], s[14:15] op_sel_hi:[1,0]
	v_pk_mul_f32 v[112:113], v[112:113], s[14:15] op_sel_hi:[1,0]
	v_pk_mul_f32 v[96:97], v[118:119], s[14:15] op_sel_hi:[1,0]
	v_pk_mul_f32 v[102:103], v[116:117], s[14:15] op_sel_hi:[1,0]
	v_pk_mul_f32 v[116:117], v[82:83], s[14:15] op_sel_hi:[1,0]
	v_pk_mul_f32 v[126:127], v[80:81], s[14:15] op_sel_hi:[1,0]
	v_pk_mul_f32 v[114:115], v[86:87], s[14:15] op_sel_hi:[1,0]
	v_pk_mul_f32 v[118:119], v[84:85], s[14:15] op_sel_hi:[1,0]
	v_pk_mul_f32 v[82:83], v[106:107], s[14:15] op_sel_hi:[1,0]
	v_pk_mul_f32 v[86:87], v[104:105], s[14:15] op_sel_hi:[1,0]
	v_pk_mul_f32 v[80:81], v[110:111], s[14:15] op_sel_hi:[1,0]
	v_pk_mul_f32 v[84:85], v[108:109], s[14:15] op_sel_hi:[1,0]
	v_pk_mul_f32 v[104:105], v[74:75], s[14:15] op_sel_hi:[1,0]
	v_pk_mul_f32 v[108:109], v[72:73], s[14:15] op_sel_hi:[1,0]
	v_pk_mul_f32 v[98:99], v[78:79], s[14:15] op_sel_hi:[1,0]
	v_pk_mul_f32 v[106:107], v[76:77], s[14:15] op_sel_hi:[1,0]
	v_pk_mul_f32 v[74:75], v[90:91], s[14:15] op_sel_hi:[1,0]
	v_pk_mul_f32 v[78:79], v[88:89], s[14:15] op_sel_hi:[1,0]
	v_pk_mul_f32 v[72:73], v[94:95], s[14:15] op_sel_hi:[1,0]
	v_pk_mul_f32 v[76:77], v[92:93], s[14:15] op_sel_hi:[1,0]
	v_pk_mul_f32 v[66:67], v[66:67], s[14:15] op_sel_hi:[1,0]
	v_pk_mul_f32 v[88:89], v[64:65], s[14:15] op_sel_hi:[1,0]
	v_pk_mul_f32 v[64:65], v[70:71], s[14:15] op_sel_hi:[1,0]
	v_pk_mul_f32 v[68:69], v[68:69], s[14:15] op_sel_hi:[1,0]
	v_pk_mul_f32 v[58:59], v[58:59], s[14:15] op_sel_hi:[1,0]
	v_pk_mul_f32 v[70:71], v[56:57], s[14:15] op_sel_hi:[1,0]
	v_pk_mul_f32 v[56:57], v[62:63], s[14:15] op_sel_hi:[1,0]
	v_pk_mul_f32 v[60:61], v[60:61], s[14:15] op_sel_hi:[1,0]
	v_pk_mul_f32 v[92:93], v[34:35], s[14:15] op_sel_hi:[1,0]
	v_pk_mul_f32 v[110:111], v[32:33], s[14:15] op_sel_hi:[1,0]
	v_pk_mul_f32 v[90:91], v[38:39], s[14:15] op_sel_hi:[1,0]
	v_pk_mul_f32 v[94:95], v[36:37], s[14:15] op_sel_hi:[1,0]
	v_pk_mul_f32 v[36:37], v[50:51], s[14:15] op_sel_hi:[1,0]
	v_pk_mul_f32 v[48:49], v[48:49], s[14:15] op_sel_hi:[1,0]
	v_pk_mul_f32 v[32:33], v[54:55], s[14:15] op_sel_hi:[1,0]
	v_pk_mul_f32 v[38:39], v[52:53], s[14:15] op_sel_hi:[1,0]
	v_pk_mul_f32 v[52:53], v[18:19], s[14:15] op_sel_hi:[1,0]
	v_pk_mul_f32 v[62:63], v[16:17], s[14:15] op_sel_hi:[1,0]
	v_pk_mul_f32 v[50:51], v[22:23], s[14:15] op_sel_hi:[1,0]
	v_pk_mul_f32 v[54:55], v[20:21], s[14:15] op_sel_hi:[1,0]
	v_pk_mul_f32 v[18:19], v[42:43], s[14:15] op_sel_hi:[1,0]
	v_pk_mul_f32 v[22:23], v[40:41], s[14:15] op_sel_hi:[1,0]
	v_pk_mul_f32 v[16:17], v[46:47], s[14:15] op_sel_hi:[1,0]
	v_pk_mul_f32 v[20:21], v[44:45], s[14:15] op_sel_hi:[1,0]
	v_pk_mul_f32 v[40:41], v[10:11], s[14:15] op_sel_hi:[1,0]
	v_pk_mul_f32 v[44:45], v[8:9], s[14:15] op_sel_hi:[1,0]
	v_pk_mul_f32 v[34:35], v[14:15], s[14:15] op_sel_hi:[1,0]
	v_pk_mul_f32 v[42:43], v[12:13], s[14:15] op_sel_hi:[1,0]
	v_pk_mul_f32 v[10:11], v[26:27], s[14:15] op_sel_hi:[1,0]
	v_pk_mul_f32 v[14:15], v[24:25], s[14:15] op_sel_hi:[1,0]
	v_pk_mul_f32 v[8:9], v[30:31], s[14:15] op_sel_hi:[1,0]
	v_pk_mul_f32 v[12:13], v[28:29], s[14:15] op_sel_hi:[1,0]
	v_pk_mul_f32 v[2:3], v[2:3], s[14:15] op_sel_hi:[1,0]
	v_pk_mul_f32 v[24:25], v[0:1], s[14:15] op_sel_hi:[1,0]
	v_pk_mul_f32 v[0:1], v[6:7], s[14:15] op_sel_hi:[1,0]
	v_pk_mul_f32 v[4:5], v[4:5], s[14:15] op_sel_hi:[1,0]
	s_and_b64 vcc, exec, s[12:13]
	s_cbranch_vccz .LBB0_575

; #define PG8_STAGE(bufoff, gbase, voff) do { _Pragma("unroll") for (int _i = 0; _i < 2; ++_i) \
;         __builtin_amdgcn_global_load_lds((const unsigned*)((const char*)(gbase) + (voff)[_i]), (LAS unsigned*)(lds + (bufoff) + ldsw + _i * 8192), 16, 0, 0); } while (0)
; #define PG8_LDA(dst, b, h) do { _Pragma("unroll") for (int m = 0; m < 4; ++m) _Pragma("unroll") for (int k = 0; k < 2; ++k) dst[m][k] = *(const LAS bf16x8*)(lds + PG8_SA(b, h) + aoff + m * 2048 + k * KOFF); } while (0)
; #define PG8_LDB(dst, b, h) do { _Pragma("unroll") for (int n = 0; n < 2; ++n) _Pragma("unroll") for (int k = 0; k < 2; ++k) dst[n][k] = *(const LAS bf16x8*)(lds + PG8_SB(b, h) + boff + n * 2048 + k * KOFF); } while (0)
; #define PG8_WAIT_V(n) asm volatile("s_waitcnt vmcnt(" #n ")" ::: "memory")
; #define PG8_WAIT_L(n) asm volatile("s_waitcnt lgkmcnt(" #n ")" ::: "memory")
; #define PG8_BAR __builtin_amdgcn_s_barrier()
; #define PG8_SCHED __builtin_amdgcn_sched_barrier(0)
; template <class Epi, bool ALIGN_EPI = true, bool FP8 = false>
; __device__ __forceinline__ void gemm_phase(LAS unsigned char* lds, const Gemm g, const StaticOrder& S, const Epi& E, const int wid) {
;     ...
;             const char* a1 = cA + (size_t)(t + 1) * kstep;
;             const char* a2 = last ? nA : cA + (size_t)(t + 2) * kstep; const char* b2 = last ? nB : cB + (size_t)(t + 2) * kstep;
;             const char* a3 = a2 + kstep; const char* b3 = b2 + kstep;
;             PG8_LDB(B0, 0, 0); PG8_LDB(B1, 0, 1); PG8_SCHED; PG8_LDA(At, 0, 0); PG8_STAGE(PG8_SA(1, 1), a1 + hstep, voffA);
;             PG8_WAIT_V(8); PG8_WAIT_L(0); PG8_BAR; PG8_MMA(0, 0, At, B0); PG8_MMA(0, 1, At, B1); PG8_BAR; PG8_SCHED;
;             PG8_LDA(At, 0, 1); PG8_STAGE(PG8_SB(0, 0), b2, voffB); PG8_STAGE(PG8_SB(0, 1), b2 + hstep, voffB); PG8_STAGE(PG8_SA(0, 0), a2, voffA);
;             PG8_WAIT_V(8); PG8_WAIT_L(0); PG8_BAR; PG8_MMA(1, 0, At, B0); PG8_MMA(1, 1, At, B1); PG8_BAR; PG8_SCHED;
.LBB0_2058:
	v_add_u32_e32 v128, s83, v192
	v_add_u32_e32 v132, s84, v192
	ds_read_b128 v[152:155], v128
	ds_read_b128 v[156:159], v128 offset:1024
	ds_read_b128 v[144:147], v128 offset:2048
	ds_read_b128 v[148:151], v128 offset:3072
	ds_read_b128 v[136:139], v132
	ds_read_b128 v[140:143], v132 offset:1024
	ds_read_b128 v[128:131], v132 offset:2048
	ds_read_b128 v[132:135], v132 offset:3072
	s_add_i32 s3, s42, 2
	s_add_u32 s43, s64, 0xfffe0080
	s_addc_u32 s52, s65, -1
	s_cmp_eq_u32 s35, s42
	s_cselect_b32 s69, s11, s52
	s_cselect_b32 s68, s16, s43
	s_cselect_b32 s67, s29, s90
	s_cselect_b32 s66, s31, s89
	v_lshl_add_u64 v[188:189], s[64:65], 0, v[174:175]
	s_add_i32 m0, s72, 0xc000
	ds_read_b128 v[180:183], v193
	ds_read_b128 v[184:187], v193 offset:1024
	ds_read_b128 v[196:199], v193 offset:2048
	ds_read_b128 v[200:203], v193 offset:3072
	ds_read_b128 v[204:207], v193 offset:4096
	ds_read_b128 v[208:211], v193 offset:5120
	ds_read_b128 v[212:215], v193 offset:6144
	ds_read_b128 v[216:219], v193 offset:7168
	global_load_lds_dwordx4 v[188:189], off
	v_lshl_add_u64 v[188:189], s[64:65], 0, v[176:177]
	s_add_i32 m0, s72, 0xe000
	s_nop 0
	global_load_lds_dwordx4 v[188:189], off
	s_setprio 1
	s_waitcnt vmcnt(8) lgkmcnt(0)
	s_barrier
	v_mfma_f32_16x16x128_f8f6f4 v[120:123], v[152:159], v[180:187], v[120:123]
	v_mfma_f32_16x16x128_f8f6f4 v[124:127], v[144:151], v[180:187], v[124:127]
	v_mfma_f32_16x16x128_f8f6f4 v[112:115], v[152:159], v[196:203], v[112:115]
	v_mfma_f32_16x16x128_f8f6f4 v[116:119], v[144:151], v[196:203], v[116:119]
	v_mfma_f32_16x16x128_f8f6f4 v[104:107], v[152:159], v[204:211], v[104:107]
	v_mfma_f32_16x16x128_f8f6f4 v[108:111], v[144:151], v[204:211], v[108:111]
	v_mfma_f32_16x16x128_f8f6f4 v[96:99], v[152:159], v[212:219], v[96:99]
	v_mfma_f32_16x16x128_f8f6f4 v[100:103], v[144:151], v[212:219], v[100:103]
	v_mfma_f32_16x16x128_f8f6f4 v[88:91], v[136:143], v[180:187], v[88:91]
	v_mfma_f32_16x16x128_f8f6f4 v[92:95], v[128:135], v[180:187], v[92:95]
	v_mfma_f32_16x16x128_f8f6f4 v[80:83], v[136:143], v[196:203], v[80:83]
	v_mfma_f32_16x16x128_f8f6f4 v[84:87], v[128:135], v[196:203], v[84:87]
	v_mfma_f32_16x16x128_f8f6f4 v[72:75], v[136:143], v[204:211], v[72:75]
	v_mfma_f32_16x16x128_f8f6f4 v[76:79], v[128:135], v[204:211], v[76:79]
	v_mfma_f32_16x16x128_f8f6f4 v[64:67], v[136:143], v[212:219], v[64:67]
	v_mfma_f32_16x16x128_f8f6f4 v[68:71], v[128:135], v[212:219], v[68:71]
	s_barrier
	s_setprio 0
	s_add_i32 s42, s83, s71
	v_lshl_add_u64 v[180:181], s[66:67], 0, v[162:163]
	s_mov_b32 m0, s42
	ds_read_b128 v[196:199], v193 offset:16384
	ds_read_b128 v[200:203], v193 offset:17408
	ds_read_b128 v[204:207], v193 offset:18432
	ds_read_b128 v[208:211], v193 offset:19456
	ds_read_b128 v[212:215], v193 offset:20480
	ds_read_b128 v[216:219], v193 offset:21504
	ds_read_b128 v[220:223], v193 offset:22528
	ds_read_b128 v[224:227], v193 offset:23552
	global_load_lds_dwordx4 v[180:181], off
	s_add_i32 m0, s42, 0x2000
	s_add_u32 s42, s66, 0x20000
	v_lshl_add_u64 v[182:183], s[66:67], 0, v[166:167]
	s_addc_u32 s43, s67, 0
	s_add_i32 s52, s84, s71
	global_load_lds_dwordx4 v[182:183], off
	v_lshl_add_u64 v[184:185], s[42:43], 0, v[162:163]
	s_mov_b32 m0, s52
	v_lshl_add_u64 v[186:187], s[68:69], 0, v[164:165]
	global_load_lds_dwordx4 v[184:185], off
	v_lshl_add_u64 v[184:185], s[42:43], 0, v[166:167]
	s_add_i32 m0, s52, 0x2000
	s_nop 0
	global_load_lds_dwordx4 v[184:185], off
	v_lshl_add_u64 v[184:185], s[68:69], 0, v[160:161]
	s_mov_b32 m0, s72
	s_nop 0
	global_load_lds_dwordx4 v[184:185], off
	s_mov_b32 m0, s73
	s_nop 0
	global_load_lds_dwordx4 v[186:187], off
	s_setprio 1
	s_waitcnt vmcnt(8) lgkmcnt(0)
	s_barrier
	v_mfma_f32_16x16x128_f8f6f4 v[56:59], v[152:159], v[196:203], v[56:59]
	v_mfma_f32_16x16x128_f8f6f4 v[60:63], v[144:151], v[196:203], v[60:63]
	v_mfma_f32_16x16x128_f8f6f4 v[48:51], v[152:159], v[204:211], v[48:51]
	v_mfma_f32_16x16x128_f8f6f4 v[52:55], v[144:151], v[204:211], v[52:55]
	v_mfma_f32_16x16x128_f8f6f4 v[40:43], v[152:159], v[212:219], v[40:43]
	v_mfma_f32_16x16x128_f8f6f4 v[44:47], v[144:151], v[212:219], v[44:47]
	v_mfma_f32_16x16x128_f8f6f4 v[188:191], v[152:159], v[220:227], v[32:35]
	v_mfma_f32_16x16x128_f8f6f4 v[228:231], v[144:151], v[220:227], v[36:39]
	v_mfma_f32_16x16x128_f8f6f4 v[232:235], v[136:143], v[196:203], v[24:27]
	v_mfma_f32_16x16x128_f8f6f4 v[236:239], v[128:135], v[196:203], v[28:31]
	v_mfma_f32_16x16x128_f8f6f4 v[240:243], v[136:143], v[204:211], v[16:19]
	v_mfma_f32_16x16x128_f8f6f4 v[204:207], v[128:135], v[204:211], v[20:23]
	v_mfma_f32_16x16x128_f8f6f4 v[208:211], v[136:143], v[212:219], v[8:11]
	v_mfma_f32_16x16x128_f8f6f4 v[212:215], v[128:135], v[212:219], v[12:15]
	v_mfma_f32_16x16x128_f8f6f4 v[216:219], v[136:143], v[220:227], v[0:3]
	v_mfma_f32_16x16x128_f8f6f4 v[220:223], v[128:135], v[220:227], v[4:7]
	s_barrier
; #define PG8_STAGE(bufoff, gbase, voff) do { _Pragma("unroll") for (int _i = 0; _i < 2; ++_i) \
;         __builtin_amdgcn_global_load_lds((const unsigned*)((const char*)(gbase) + (voff)[_i]), (LAS unsigned*)(lds + (bufoff) + ldsw + _i * 8192), 16, 0, 0); } while (0)
; #define PG8_LDA(dst, b, h) do { _Pragma("unroll") for (int m = 0; m < 4; ++m) _Pragma("unroll") for (int k = 0; k < 2; ++k) dst[m][k] = *(const LAS bf16x8*)(lds + PG8_SA(b, h) + aoff + m * 2048 + k * KOFF); } while (0)
; #define PG8_LDB(dst, b, h) do { _Pragma("unroll") for (int n = 0; n < 2; ++n) _Pragma("unroll") for (int k = 0; k < 2; ++k) dst[n][k] = *(const LAS bf16x8*)(lds + PG8_SB(b, h) + boff + n * 2048 + k * KOFF); } while (0)
; #define PG8_WAIT_V(n) asm volatile("s_waitcnt vmcnt(" #n ")" ::: "memory")
; #define PG8_WAIT_L(n) asm volatile("s_waitcnt lgkmcnt(" #n ")" ::: "memory")
; #define PG8_BAR __builtin_amdgcn_s_barrier()
; #define PG8_SCHED __builtin_amdgcn_sched_barrier(0)
; template <class Epi, bool ALIGN_EPI = true, bool FP8 = false>
; __device__ __forceinline__ void gemm_phase(LAS unsigned char* lds, const Gemm g, const StaticOrder& S, const Epi& E, const int wid) {
;     ...
;             PG8_LDB(B0, 1, 0); PG8_LDB(B1, 1, 1); PG8_SCHED; PG8_LDA(At, 1, 0); PG8_STAGE(PG8_SA(0, 1), a2 + hstep, voffA);
;             PG8_WAIT_V(8); PG8_WAIT_L(0); PG8_BAR; PG8_MMA(0, 0, At, B0); PG8_MMA(0, 1, At, B1); PG8_BAR; PG8_SCHED;
;             PG8_LDA(At, 1, 1); PG8_STAGE(PG8_SB(1, 0), b3, voffB); PG8_STAGE(PG8_SB(1, 1), b3 + hstep, voffB); PG8_STAGE(PG8_SA(1, 0), a3, voffA);
;             PG8_WAIT_V(8); PG8_WAIT_L(0); PG8_BAR; PG8_MMA(1, 0, At, B0); PG8_MMA(1, 1, At, B1); PG8_BAR; PG8_SCHED;
;         }
;         if constexpr (ALIGN_EPI) { if (wr == 0) PG8_BAR; }
	s_setprio 0
	s_add_i32 s52, 0, 0x18000
	s_add_i32 s54, 0, 0x1c000
	s_nop 0
	v_add_u32_e32 v12, s52, v192
	v_add_u32_e32 v16, s54, v192
	ds_read_b128 v[0:3], v12
	ds_read_b128 v[4:7], v12 offset:1024
	ds_read_b128 v[8:11], v12 offset:2048
	ds_read_b128 v[12:15], v12 offset:3072
	ds_read_b128 v[128:131], v16
	ds_read_b128 v[132:135], v16 offset:1024
	ds_read_b128 v[136:139], v16 offset:2048
	ds_read_b128 v[140:143], v16 offset:3072
	s_add_u32 s42, s68, 0x20000
	s_addc_u32 s43, s69, 0
	s_mov_b32 m0, s74
	v_lshl_add_u64 v[152:153], s[42:43], 0, v[160:161]
	ds_read_b128 v[16:19], v193 offset:32768
	ds_read_b128 v[20:23], v193 offset:33792
	ds_read_b128 v[24:27], v193 offset:34816
	ds_read_b128 v[28:31], v193 offset:35840
	ds_read_b128 v[32:35], v193 offset:36864
	ds_read_b128 v[36:39], v193 offset:37888
	ds_read_b128 v[144:147], v193 offset:38912
	ds_read_b128 v[148:151], v193 offset:39936
	global_load_lds_dwordx4 v[152:153], off
	v_lshl_add_u64 v[152:153], s[42:43], 0, v[164:165]
	s_mov_b32 m0, s75
	s_nop 0
	global_load_lds_dwordx4 v[152:153], off
	s_setprio 1
	s_waitcnt vmcnt(8) lgkmcnt(0)
	s_barrier
	v_mfma_f32_16x16x128_f8f6f4 v[120:123], v[0:7], v[16:23], v[120:123]
	v_mfma_f32_16x16x128_f8f6f4 v[124:127], v[8:15], v[16:23], v[124:127]
	v_mfma_f32_16x16x128_f8f6f4 v[112:115], v[0:7], v[24:31], v[112:115]
	v_mfma_f32_16x16x128_f8f6f4 v[116:119], v[8:15], v[24:31], v[116:119]
	v_mfma_f32_16x16x128_f8f6f4 v[104:107], v[0:7], v[32:39], v[104:107]
	v_mfma_f32_16x16x128_f8f6f4 v[108:111], v[8:15], v[32:39], v[108:111]
	v_mfma_f32_16x16x128_f8f6f4 v[96:99], v[0:7], v[144:151], v[96:99]
	v_mfma_f32_16x16x128_f8f6f4 v[100:103], v[8:15], v[144:151], v[100:103]
	v_mfma_f32_16x16x128_f8f6f4 v[88:91], v[128:135], v[16:23], v[88:91]
	v_mfma_f32_16x16x128_f8f6f4 v[92:95], v[136:143], v[16:23], v[92:95]
	v_mfma_f32_16x16x128_f8f6f4 v[80:83], v[128:135], v[24:31], v[80:83]
	v_mfma_f32_16x16x128_f8f6f4 v[84:87], v[136:143], v[24:31], v[84:87]
	v_mfma_f32_16x16x128_f8f6f4 v[72:75], v[128:135], v[32:39], v[72:75]
	v_mfma_f32_16x16x128_f8f6f4 v[76:79], v[136:143], v[32:39], v[76:79]
	v_mfma_f32_16x16x128_f8f6f4 v[64:67], v[128:135], v[144:151], v[64:67]
	v_mfma_f32_16x16x128_f8f6f4 v[68:71], v[136:143], v[144:151], v[68:71]
	s_barrier
	s_setprio 0
	s_add_i32 s42, s52, s71
	v_lshl_add_u64 v[24:25], v[180:181], 0, s[20:21]
	s_mov_b32 m0, s42
	ds_read_b128 v[16:19], v193 offset:49152
	ds_read_b128 v[20:23], v193 offset:50176
	ds_read_b128 v[144:147], v193 offset:51200
	ds_read_b128 v[148:151], v193 offset:52224
	ds_read_b128 v[152:155], v193 offset:53248
	ds_read_b128 v[156:159], v193 offset:54272
	ds_read_b128 v[196:199], v193 offset:55296
	ds_read_b128 v[200:203], v193 offset:56320
	global_load_lds_dwordx4 v[24:25], off
	s_add_i32 m0, s42, 0x2000
	s_add_u32 s42, s66, 0x20080
	v_lshl_add_u64 v[24:25], v[182:183], 0, s[20:21]
	s_addc_u32 s43, s67, 0
	s_add_i32 s52, s54, s71
	global_load_lds_dwordx4 v[24:25], off
	v_lshl_add_u64 v[24:25], s[42:43], 0, v[162:163]
	s_mov_b32 m0, s52
	s_nop 0
	global_load_lds_dwordx4 v[24:25], off
	v_lshl_add_u64 v[24:25], s[42:43], 0, v[166:167]
	s_add_i32 m0, s52, 0x2000
	s_nop 0
	global_load_lds_dwordx4 v[24:25], off
	v_lshl_add_u64 v[24:25], v[184:185], 0, s[20:21]
	s_mov_b32 m0, s80
	s_nop 0
	global_load_lds_dwordx4 v[24:25], off
	v_lshl_add_u64 v[24:25], v[186:187], 0, s[20:21]
	s_mov_b32 m0, s81
	s_nop 0
	global_load_lds_dwordx4 v[24:25], off
	s_setprio 1
	s_waitcnt vmcnt(8) lgkmcnt(0)
	s_barrier
	v_mfma_f32_16x16x128_f8f6f4 v[56:59], v[0:7], v[16:23], v[56:59]
	v_mfma_f32_16x16x128_f8f6f4 v[60:63], v[8:15], v[16:23], v[60:63]
	v_mfma_f32_16x16x128_f8f6f4 v[48:51], v[0:7], v[144:151], v[48:51]
	v_mfma_f32_16x16x128_f8f6f4 v[52:55], v[8:15], v[144:151], v[52:55]
	v_mfma_f32_16x16x128_f8f6f4 v[40:43], v[0:7], v[152:159], v[40:43]
	v_mfma_f32_16x16x128_f8f6f4 v[44:47], v[8:15], v[152:159], v[44:47]
	v_mfma_f32_16x16x128_f8f6f4 v[32:35], v[0:7], v[196:203], v[188:191]
	v_mfma_f32_16x16x128_f8f6f4 v[36:39], v[8:15], v[196:203], v[228:231]
	v_mfma_f32_16x16x128_f8f6f4 v[24:27], v[128:135], v[16:23], v[232:235]
	v_mfma_f32_16x16x128_f8f6f4 v[28:31], v[136:143], v[16:23], v[236:239]
	v_mfma_f32_16x16x128_f8f6f4 v[16:19], v[128:135], v[144:151], v[240:243]
	v_mfma_f32_16x16x128_f8f6f4 v[20:23], v[136:143], v[144:151], v[204:207]
	v_mfma_f32_16x16x128_f8f6f4 v[8:11], v[128:135], v[152:159], v[208:211]
	v_mfma_f32_16x16x128_f8f6f4 v[12:15], v[136:143], v[152:159], v[212:215]
	v_mfma_f32_16x16x128_f8f6f4 v[0:3], v[128:135], v[196:203], v[216:219]
	v_mfma_f32_16x16x128_f8f6f4 v[4:7], v[136:143], v[196:203], v[220:223]
	s_barrier
	s_setprio 0
	s_add_u32 s64, s64, 0x100
	s_addc_u32 s65, s65, 0
	s_add_u32 s89, s89, 0x100
	s_addc_u32 s90, s90, 0
	s_cmp_ge_u32 s3, s9
	s_mov_b32 s42, s3
	s_cbranch_scc0 .LBB0_2058
	s_and_b64 vcc, exec, s[22:23]
	s_cbranch_vccz .LBB0_2061
	s_barrier

; #define PG8_STAGE(bufoff, gbase, voff) do { _Pragma("unroll") for (int _i = 0; _i < 2; ++_i) \
;         __builtin_amdgcn_global_load_lds((const unsigned*)((const char*)(gbase) + (voff)[_i]), (LAS unsigned*)(lds + (bufoff) + ldsw + _i * 8192), 16, 0, 0); } while (0)
; #define PG8_LDA(dst, b, h) do { _Pragma("unroll") for (int m = 0; m < 4; ++m) _Pragma("unroll") for (int k = 0; k < 2; ++k) dst[m][k] = *(const LAS bf16x8*)(lds + PG8_SA(b, h) + aoff + m * 2048 + k * KOFF); } while (0)
; #define PG8_LDB(dst, b, h) do { _Pragma("unroll") for (int n = 0; n < 2; ++n) _Pragma("unroll") for (int k = 0; k < 2; ++k) dst[n][k] = *(const LAS bf16x8*)(lds + PG8_SB(b, h) + boff + n * 2048 + k * KOFF); } while (0)
; #define PG8_WAIT_V(n) asm volatile("s_waitcnt vmcnt(" #n ")" ::: "memory")
; #define PG8_WAIT_L(n) asm volatile("s_waitcnt lgkmcnt(" #n ")" ::: "memory")
; #define PG8_BAR __builtin_amdgcn_s_barrier()
; #define PG8_SCHED __builtin_amdgcn_sched_barrier(0)
; template <class Epi, bool ALIGN_EPI = true, bool FP8 = false>
; __device__ __forceinline__ void gemm_phase(LAS unsigned char* lds, const Gemm g, const StaticOrder& S, const Epi& E, const int wid) {
;     ...
;             const char* a1 = cA + (size_t)(t + 1) * kstep;
;             const char* a2 = last ? nA : cA + (size_t)(t + 2) * kstep; const char* b2 = last ? nB : cB + (size_t)(t + 2) * kstep;
;             const char* a3 = a2 + kstep; const char* b3 = b2 + kstep;
;             PG8_LDB(B0, 0, 0); PG8_LDB(B1, 0, 1); PG8_SCHED; PG8_LDA(At, 0, 0); PG8_STAGE(PG8_SA(1, 1), a1 + hstep, voffA);
;             PG8_WAIT_V(8); PG8_WAIT_L(0); PG8_BAR; PG8_MMA(0, 0, At, B0); PG8_MMA(0, 1, At, B1); PG8_BAR; PG8_SCHED;
;             PG8_LDA(At, 0, 1); PG8_STAGE(PG8_SB(0, 0), b2, voffB); PG8_STAGE(PG8_SB(0, 1), b2 + hstep, voffB); PG8_STAGE(PG8_SA(0, 0), a2, voffA);
;             PG8_WAIT_V(8); PG8_WAIT_L(0); PG8_BAR; PG8_MMA(1, 0, At, B0); PG8_MMA(1, 1, At, B1); PG8_BAR; PG8_SCHED;
.LBB0_2290:
	ds_read_b128 v[152:155], v218
	ds_read_b128 v[156:159], v218 offset:1024
	ds_read_b128 v[144:147], v218 offset:2048
	ds_read_b128 v[148:151], v218 offset:3072
	ds_read_b128 v[136:139], v219
	ds_read_b128 v[140:143], v219 offset:1024
	ds_read_b128 v[128:131], v219 offset:2048
	ds_read_b128 v[132:135], v219 offset:3072
	s_add_i32 s3, s38, 2
	s_add_u32 s36, s34, 0xfffc0080
	s_addc_u32 s37, s35, -1
	s_cmp_eq_u32 s88, s38
	s_cselect_b32 s38, s31, s36
	s_cselect_b32 s39, s21, s37
	s_cselect_b32 s37, s19, s90
	s_cselect_b32 s36, s87, s89
	v_lshl_add_u64 v[212:213], s[34:35], 0, v[198:199]
	s_add_i32 m0, s27, 0xc000
	ds_read_b128 v[160:163], v220
	ds_read_b128 v[164:167], v220 offset:1024
	ds_read_b128 v[168:171], v220 offset:2048
	ds_read_b128 v[172:175], v220 offset:3072
	ds_read_b128 v[176:179], v220 offset:4096
	ds_read_b128 v[180:183], v220 offset:5120
	ds_read_b128 v[204:207], v220 offset:6144
	ds_read_b128 v[208:211], v220 offset:7168
	global_load_lds_dwordx4 v[212:213], off
	v_lshl_add_u64 v[212:213], s[34:35], 0, v[200:201]
	s_add_i32 m0, s27, 0xe000
	s_nop 0
	global_load_lds_dwordx4 v[212:213], off
	s_setprio 1
	s_waitcnt vmcnt(8) lgkmcnt(0)
	s_barrier
	v_mfma_f32_16x16x128_f8f6f4 v[120:123], v[152:159], v[160:167], v[120:123]
	v_mfma_f32_16x16x128_f8f6f4 v[124:127], v[144:151], v[160:167], v[124:127]
	v_mfma_f32_16x16x128_f8f6f4 v[104:107], v[152:159], v[168:175], v[104:107]
	v_mfma_f32_16x16x128_f8f6f4 v[108:111], v[144:151], v[168:175], v[108:111]
	v_mfma_f32_16x16x128_f8f6f4 v[96:99], v[152:159], v[176:183], v[96:99]
	v_mfma_f32_16x16x128_f8f6f4 v[100:103], v[144:151], v[176:183], v[100:103]
	v_mfma_f32_16x16x128_f8f6f4 v[80:83], v[152:159], v[204:211], v[80:83]
	v_mfma_f32_16x16x128_f8f6f4 v[84:87], v[144:151], v[204:211], v[84:87]
	v_mfma_f32_16x16x128_f8f6f4 v[112:115], v[136:143], v[160:167], v[112:115]
	v_mfma_f32_16x16x128_f8f6f4 v[116:119], v[128:135], v[160:167], v[116:119]
	v_mfma_f32_16x16x128_f8f6f4 v[88:91], v[136:143], v[168:175], v[88:91]
	v_mfma_f32_16x16x128_f8f6f4 v[92:95], v[128:135], v[168:175], v[92:95]
	v_mfma_f32_16x16x128_f8f6f4 v[72:75], v[136:143], v[176:183], v[72:75]
	v_mfma_f32_16x16x128_f8f6f4 v[76:79], v[128:135], v[176:183], v[76:79]
	v_mfma_f32_16x16x128_f8f6f4 v[64:67], v[136:143], v[204:211], v[64:67]
	v_mfma_f32_16x16x128_f8f6f4 v[68:71], v[128:135], v[204:211], v[68:71]
	s_barrier
	s_setprio 0
	s_add_i32 s42, s75, s53
	v_lshl_add_u64 v[160:161], s[36:37], 0, v[188:189]
	s_mov_b32 m0, s42
	ds_read_b128 v[168:171], v220 offset:16384
	ds_read_b128 v[172:175], v220 offset:17408
	ds_read_b128 v[176:179], v220 offset:18432
	ds_read_b128 v[180:183], v220 offset:19456
	ds_read_b128 v[204:207], v220 offset:20480
	ds_read_b128 v[208:211], v220 offset:21504
	ds_read_b128 v[222:225], v220 offset:22528
	ds_read_b128 v[226:229], v220 offset:23552
	global_load_lds_dwordx4 v[160:161], off
	s_add_i32 m0, s42, 0x2000
	s_add_u32 s42, s36, 0x40000
	v_lshl_add_u64 v[162:163], s[36:37], 0, v[184:185]
	s_addc_u32 s43, s37, 0
	s_add_i32 s52, s76, s53
	global_load_lds_dwordx4 v[162:163], off
	v_lshl_add_u64 v[164:165], s[42:43], 0, v[188:189]
	s_mov_b32 m0, s52
	v_lshl_add_u64 v[166:167], s[38:39], 0, v[186:187]
	global_load_lds_dwordx4 v[164:165], off
	v_lshl_add_u64 v[164:165], s[42:43], 0, v[184:185]
	s_add_i32 m0, s52, 0x2000
	s_nop 0
	global_load_lds_dwordx4 v[164:165], off
	v_lshl_add_u64 v[164:165], s[38:39], 0, v[190:191]
	s_mov_b32 m0, s27
	s_nop 0
	global_load_lds_dwordx4 v[164:165], off
	s_mov_b32 m0, s55
	s_nop 0
	global_load_lds_dwordx4 v[166:167], off
	s_setprio 1
	s_waitcnt vmcnt(8) lgkmcnt(0)
	s_barrier
	v_mfma_f32_16x16x128_f8f6f4 v[56:59], v[152:159], v[168:175], v[56:59]
	v_mfma_f32_16x16x128_f8f6f4 v[60:63], v[144:151], v[168:175], v[60:63]
	v_mfma_f32_16x16x128_f8f6f4 v[48:51], v[152:159], v[176:183], v[48:51]
	v_mfma_f32_16x16x128_f8f6f4 v[52:55], v[144:151], v[176:183], v[52:55]
	v_mfma_f32_16x16x128_f8f6f4 v[32:35], v[152:159], v[204:211], v[32:35]
	v_mfma_f32_16x16x128_f8f6f4 v[212:215], v[144:151], v[204:211], v[36:39]
	v_mfma_f32_16x16x128_f8f6f4 v[230:233], v[152:159], v[222:229], v[16:19]
	v_mfma_f32_16x16x128_f8f6f4 v[234:237], v[144:151], v[222:229], v[20:23]
	v_mfma_f32_16x16x128_f8f6f4 v[44:47], v[128:135], v[168:175], v[44:47]
	v_mfma_f32_16x16x128_f8f6f4 v[238:241], v[136:143], v[168:175], v[40:43]
	v_mfma_f32_16x16x128_f8f6f4 v[242:245], v[136:143], v[176:183], v[24:27]
	v_mfma_f32_16x16x128_f8f6f4 v[176:179], v[128:135], v[176:183], v[28:31]
	v_mfma_f32_16x16x128_f8f6f4 v[180:183], v[136:143], v[204:211], v[8:11]
	v_mfma_f32_16x16x128_f8f6f4 v[204:207], v[128:135], v[204:211], v[12:15]
	v_mfma_f32_16x16x128_f8f6f4 v[208:211], v[136:143], v[222:229], v[0:3]
	v_mfma_f32_16x16x128_f8f6f4 v[222:225], v[128:135], v[222:229], v[4:7]
	s_barrier
; #define PG8_STAGE(bufoff, gbase, voff) do { _Pragma("unroll") for (int _i = 0; _i < 2; ++_i) \
;         __builtin_amdgcn_global_load_lds((const unsigned*)((const char*)(gbase) + (voff)[_i]), (LAS unsigned*)(lds + (bufoff) + ldsw + _i * 8192), 16, 0, 0); } while (0)
; #define PG8_LDA(dst, b, h) do { _Pragma("unroll") for (int m = 0; m < 4; ++m) _Pragma("unroll") for (int k = 0; k < 2; ++k) dst[m][k] = *(const LAS bf16x8*)(lds + PG8_SA(b, h) + aoff + m * 2048 + k * KOFF); } while (0)
; #define PG8_LDB(dst, b, h) do { _Pragma("unroll") for (int n = 0; n < 2; ++n) _Pragma("unroll") for (int k = 0; k < 2; ++k) dst[n][k] = *(const LAS bf16x8*)(lds + PG8_SB(b, h) + boff + n * 2048 + k * KOFF); } while (0)
; #define PG8_WAIT_V(n) asm volatile("s_waitcnt vmcnt(" #n ")" ::: "memory")
; #define PG8_WAIT_L(n) asm volatile("s_waitcnt lgkmcnt(" #n ")" ::: "memory")
; #define PG8_BAR __builtin_amdgcn_s_barrier()
; #define PG8_SCHED __builtin_amdgcn_sched_barrier(0)
; template <class Epi, bool ALIGN_EPI = true, bool FP8 = false>
; __device__ __forceinline__ void gemm_phase(LAS unsigned char* lds, const Gemm g, const StaticOrder& S, const Epi& E, const int wid) {
;     ...
;             PG8_LDB(B0, 1, 0); PG8_LDB(B1, 1, 1); PG8_SCHED; PG8_LDA(At, 1, 0); PG8_STAGE(PG8_SA(0, 1), a2 + hstep, voffA);
;             PG8_WAIT_V(8); PG8_WAIT_L(0); PG8_BAR; PG8_MMA(0, 0, At, B0); PG8_MMA(0, 1, At, B1); PG8_BAR; PG8_SCHED;
;             PG8_LDA(At, 1, 1); PG8_STAGE(PG8_SB(1, 0), b3, voffB); PG8_STAGE(PG8_SB(1, 1), b3 + hstep, voffB); PG8_STAGE(PG8_SA(1, 0), a3, voffA);
;             PG8_WAIT_V(8); PG8_WAIT_L(0); PG8_BAR; PG8_MMA(1, 0, At, B0); PG8_MMA(1, 1, At, B1); PG8_BAR; PG8_SCHED;
;         }
;         if constexpr (ALIGN_EPI) { if (wr == 0) PG8_BAR; }
	s_setprio 0
	s_add_i32 s42, 0, 0x18000
	s_add_i32 s43, 0, 0x1c000
	s_nop 0
	v_add_u32_e32 v12, s42, v217
	v_add_u32_e32 v16, s43, v217
	ds_read_b128 v[0:3], v12
	ds_read_b128 v[4:7], v12 offset:1024
	ds_read_b128 v[8:11], v12 offset:2048
	ds_read_b128 v[12:15], v12 offset:3072
	ds_read_b128 v[128:131], v16
	ds_read_b128 v[132:135], v16 offset:1024
	ds_read_b128 v[136:139], v16 offset:2048
	ds_read_b128 v[140:143], v16 offset:3072
	s_add_u32 s38, s38, 0x40000
	s_addc_u32 s39, s39, 0
	s_mov_b32 m0, s64
	v_lshl_add_u64 v[152:153], s[38:39], 0, v[190:191]
	ds_read_b128 v[16:19], v220 offset:32768
	ds_read_b128 v[20:23], v220 offset:33792
	ds_read_b128 v[24:27], v220 offset:34816
	ds_read_b128 v[28:31], v220 offset:35840
	ds_read_b128 v[36:39], v220 offset:36864
	ds_read_b128 v[40:43], v220 offset:37888
	ds_read_b128 v[144:147], v220 offset:38912
	ds_read_b128 v[148:151], v220 offset:39936
	global_load_lds_dwordx4 v[152:153], off
	v_lshl_add_u64 v[152:153], s[38:39], 0, v[186:187]
	s_mov_b32 m0, s65
	s_nop 0
	global_load_lds_dwordx4 v[152:153], off
	s_setprio 1
	s_waitcnt vmcnt(8) lgkmcnt(0)
	s_barrier
	v_mfma_f32_16x16x128_f8f6f4 v[120:123], v[0:7], v[16:23], v[120:123]
	v_mfma_f32_16x16x128_f8f6f4 v[124:127], v[8:15], v[16:23], v[124:127]
	v_mfma_f32_16x16x128_f8f6f4 v[104:107], v[0:7], v[24:31], v[104:107]
	v_mfma_f32_16x16x128_f8f6f4 v[108:111], v[8:15], v[24:31], v[108:111]
	v_mfma_f32_16x16x128_f8f6f4 v[96:99], v[0:7], v[36:43], v[96:99]
	v_mfma_f32_16x16x128_f8f6f4 v[100:103], v[8:15], v[36:43], v[100:103]
	v_mfma_f32_16x16x128_f8f6f4 v[80:83], v[0:7], v[144:151], v[80:83]
	v_mfma_f32_16x16x128_f8f6f4 v[84:87], v[8:15], v[144:151], v[84:87]
	v_mfma_f32_16x16x128_f8f6f4 v[112:115], v[128:135], v[16:23], v[112:115]
	v_mfma_f32_16x16x128_f8f6f4 v[116:119], v[136:143], v[16:23], v[116:119]
	v_mfma_f32_16x16x128_f8f6f4 v[88:91], v[128:135], v[24:31], v[88:91]
	v_mfma_f32_16x16x128_f8f6f4 v[92:95], v[136:143], v[24:31], v[92:95]
	v_mfma_f32_16x16x128_f8f6f4 v[72:75], v[128:135], v[36:43], v[72:75]
	v_mfma_f32_16x16x128_f8f6f4 v[76:79], v[136:143], v[36:43], v[76:79]
	v_mfma_f32_16x16x128_f8f6f4 v[64:67], v[128:135], v[144:151], v[64:67]
	v_mfma_f32_16x16x128_f8f6f4 v[68:71], v[136:143], v[144:151], v[68:71]
	s_barrier
	s_setprio 0
	s_add_i32 s38, s42, s53
	v_lshl_add_u64 v[16:17], v[160:161], 0, s[14:15]
	s_mov_b32 m0, s38
	ds_read_b128 v[24:27], v220 offset:49152
	ds_read_b128 v[28:31], v220 offset:50176
	ds_read_b128 v[144:147], v220 offset:51200
	ds_read_b128 v[148:151], v220 offset:52224
	ds_read_b128 v[152:155], v220 offset:53248
	ds_read_b128 v[156:159], v220 offset:54272
	ds_read_b128 v[168:171], v220 offset:55296
	ds_read_b128 v[172:175], v220 offset:56320
	global_load_lds_dwordx4 v[16:17], off
	s_add_i32 m0, s38, 0x2000
	s_add_u32 s36, s36, 0x40080
	v_lshl_add_u64 v[16:17], v[162:163], 0, s[14:15]
	s_addc_u32 s37, s37, 0
	s_add_i32 s38, s43, s53
	global_load_lds_dwordx4 v[16:17], off
	v_lshl_add_u64 v[16:17], s[36:37], 0, v[188:189]
	s_mov_b32 m0, s38
	s_nop 0
	global_load_lds_dwordx4 v[16:17], off
	v_lshl_add_u64 v[16:17], s[36:37], 0, v[184:185]
	s_add_i32 m0, s38, 0x2000
	s_nop 0
	global_load_lds_dwordx4 v[16:17], off
	v_lshl_add_u64 v[16:17], v[164:165], 0, s[14:15]
	s_mov_b32 m0, s71
	s_nop 0
	global_load_lds_dwordx4 v[16:17], off
	v_lshl_add_u64 v[16:17], v[166:167], 0, s[14:15]
	s_mov_b32 m0, s72
	s_nop 0
	global_load_lds_dwordx4 v[16:17], off
	s_setprio 1
	s_waitcnt vmcnt(8) lgkmcnt(0)
	s_barrier
	v_mfma_f32_16x16x128_f8f6f4 v[56:59], v[0:7], v[24:31], v[56:59]
	v_mfma_f32_16x16x128_f8f6f4 v[60:63], v[8:15], v[24:31], v[60:63]
	v_mfma_f32_16x16x128_f8f6f4 v[48:51], v[0:7], v[144:151], v[48:51]
	v_mfma_f32_16x16x128_f8f6f4 v[52:55], v[8:15], v[144:151], v[52:55]
	v_mfma_f32_16x16x128_f8f6f4 v[32:35], v[0:7], v[152:159], v[32:35]
	v_mfma_f32_16x16x128_f8f6f4 v[36:39], v[8:15], v[152:159], v[212:215]
	v_mfma_f32_16x16x128_f8f6f4 v[16:19], v[0:7], v[168:175], v[230:233]
	v_mfma_f32_16x16x128_f8f6f4 v[20:23], v[8:15], v[168:175], v[234:237]
	v_mfma_f32_16x16x128_f8f6f4 v[40:43], v[128:135], v[24:31], v[238:241]
	v_mfma_f32_16x16x128_f8f6f4 v[44:47], v[136:143], v[24:31], v[44:47]
	v_mfma_f32_16x16x128_f8f6f4 v[24:27], v[128:135], v[144:151], v[242:245]
	v_mfma_f32_16x16x128_f8f6f4 v[28:31], v[136:143], v[144:151], v[176:179]
	v_mfma_f32_16x16x128_f8f6f4 v[8:11], v[128:135], v[152:159], v[180:183]
	v_mfma_f32_16x16x128_f8f6f4 v[12:15], v[136:143], v[152:159], v[204:207]
	v_mfma_f32_16x16x128_f8f6f4 v[0:3], v[128:135], v[168:175], v[208:211]
	v_mfma_f32_16x16x128_f8f6f4 v[4:7], v[136:143], v[168:175], v[222:225]
	s_barrier
	s_setprio 0
	s_add_u32 s34, s34, 0x100
	s_addc_u32 s35, s35, 0
	s_add_u32 s89, s89, 0x100
	s_addc_u32 s90, s90, 0
	s_cmp_ge_u32 s3, s29
	s_mov_b32 s38, s3
	s_cbranch_scc0 .LBB0_2290
	s_and_b64 vcc, exec, s[12:13]
	s_cbranch_vccz .LBB0_2293
	s_barrier

; #define PG8_STAGE(bufoff, gbase, voff) do { _Pragma("unroll") for (int _i = 0; _i < 2; ++_i) \
;         __builtin_amdgcn_global_load_lds((const unsigned*)((const char*)(gbase) + (voff)[_i]), (LAS unsigned*)(lds + (bufoff) + ldsw + _i * 8192), 16, 0, 0); } while (0)
; #define PG8_LDA(dst, b, h) do { _Pragma("unroll") for (int m = 0; m < 4; ++m) _Pragma("unroll") for (int k = 0; k < 2; ++k) dst[m][k] = *(const LAS bf16x8*)(lds + PG8_SA(b, h) + aoff + m * 2048 + k * KOFF); } while (0)
; #define PG8_LDB(dst, b, h) do { _Pragma("unroll") for (int n = 0; n < 2; ++n) _Pragma("unroll") for (int k = 0; k < 2; ++k) dst[n][k] = *(const LAS bf16x8*)(lds + PG8_SB(b, h) + boff + n * 2048 + k * KOFF); } while (0)
; #define PG8_WAIT_V(n) asm volatile("s_waitcnt vmcnt(" #n ")" ::: "memory")
; #define PG8_WAIT_L(n) asm volatile("s_waitcnt lgkmcnt(" #n ")" ::: "memory")
; #define PG8_BAR __builtin_amdgcn_s_barrier()
; #define PG8_SCHED __builtin_amdgcn_sched_barrier(0)
; template <class Epi, bool ALIGN_EPI = true, bool FP8 = false>
; __device__ __forceinline__ void gemm_phase(LAS unsigned char* lds, const Gemm g, const StaticOrder& S, const Epi& E, const int wid) {
;     ...
;             const char* a1 = cA + (size_t)(t + 1) * kstep;
;             const char* a2 = last ? nA : cA + (size_t)(t + 2) * kstep; const char* b2 = last ? nB : cB + (size_t)(t + 2) * kstep;
;             const char* a3 = a2 + kstep; const char* b3 = b2 + kstep;
;             PG8_LDB(B0, 0, 0); PG8_LDB(B1, 0, 1); PG8_SCHED; PG8_LDA(At, 0, 0); PG8_STAGE(PG8_SA(1, 1), a1 + hstep, voffA);
;             PG8_WAIT_V(8); PG8_WAIT_L(0); PG8_BAR; PG8_MMA(0, 0, At, B0); PG8_MMA(0, 1, At, B1); PG8_BAR; PG8_SCHED;
;             PG8_LDA(At, 0, 1); PG8_STAGE(PG8_SB(0, 0), b2, voffB); PG8_STAGE(PG8_SB(0, 1), b2 + hstep, voffB); PG8_STAGE(PG8_SA(0, 0), a2, voffA);
.LBB0_2452:
	ds_read_b128 v[152:155], v148
	ds_read_b128 v[156:159], v148 offset:1024
	ds_read_b128 v[160:163], v148 offset:2048
	ds_read_b128 v[164:167], v148 offset:3072
	ds_read_b128 v[168:171], v149
	ds_read_b128 v[172:175], v149 offset:1024
	ds_read_b128 v[176:179], v149 offset:2048
	ds_read_b128 v[180:183], v149 offset:3072
	s_add_i32 s76, s30, 2
	s_add_u32 s31, s28, 0xfff80080
	s_addc_u32 s34, s29, -1
	s_cmp_eq_u32 s43, s30
	s_cselect_b32 s30, s42, s52
	s_cselect_b32 s35, s3, s34
	s_cselect_b32 s34, s17, s31
	s_cselect_b32 s31, s19, s75
	v_lshl_add_u64 v[144:145], s[28:29], 0, v[138:139]
	s_add_i32 m0, s25, 0xc000
	ds_read_b128 v[184:187], v150
	ds_read_b128 v[188:191], v150 offset:1024
	ds_read_b128 v[192:195], v150 offset:2048
	ds_read_b128 v[196:199], v150 offset:3072
	ds_read_b128 v[200:203], v150 offset:4096
	ds_read_b128 v[204:207], v150 offset:5120
	ds_read_b128 v[208:211], v150 offset:6144
	ds_read_b128 v[212:215], v150 offset:7168
	global_load_lds_dwordx4 v[144:145], off
	v_lshl_add_u64 v[144:145], s[28:29], 0, v[140:141]
	s_add_i32 m0, s25, 0xe000
	s_nop 0
	global_load_lds_dwordx4 v[144:145], off
	s_setprio 1
	s_waitcnt vmcnt(8) lgkmcnt(0)
	s_barrier
	v_mfma_f32_16x16x32_bf16 v[124:127], v[152:155], v[184:187], v[124:127]
	v_mfma_f32_16x16x32_bf16 v[116:119], v[160:163], v[184:187], v[116:119]
	v_mfma_f32_16x16x32_bf16 v[108:111], v[152:155], v[192:195], v[108:111]
	v_mfma_f32_16x16x32_bf16 v[100:103], v[160:163], v[192:195], v[100:103]
	v_mfma_f32_16x16x32_bf16 v[92:95], v[152:155], v[200:203], v[92:95]
	v_mfma_f32_16x16x32_bf16 v[84:87], v[160:163], v[200:203], v[84:87]
	v_mfma_f32_16x16x32_bf16 v[76:79], v[152:155], v[208:211], v[76:79]
	v_mfma_f32_16x16x32_bf16 v[68:71], v[160:163], v[208:211], v[68:71]
	v_mfma_f32_16x16x32_bf16 v[124:127], v[156:159], v[188:191], v[124:127]
	v_mfma_f32_16x16x32_bf16 v[116:119], v[164:167], v[188:191], v[116:119]
	v_mfma_f32_16x16x32_bf16 v[108:111], v[156:159], v[196:199], v[108:111]
	v_mfma_f32_16x16x32_bf16 v[100:103], v[164:167], v[196:199], v[100:103]
	v_mfma_f32_16x16x32_bf16 v[92:95], v[156:159], v[204:207], v[92:95]
	v_mfma_f32_16x16x32_bf16 v[84:87], v[164:167], v[204:207], v[84:87]
	v_mfma_f32_16x16x32_bf16 v[76:79], v[156:159], v[212:215], v[76:79]
	v_mfma_f32_16x16x32_bf16 v[68:71], v[164:167], v[212:215], v[68:71]
	v_mfma_f32_16x16x32_bf16 v[120:123], v[168:171], v[184:187], v[120:123]
	v_mfma_f32_16x16x32_bf16 v[112:115], v[176:179], v[184:187], v[112:115]
	v_mfma_f32_16x16x32_bf16 v[104:107], v[168:171], v[192:195], v[104:107]
	v_mfma_f32_16x16x32_bf16 v[96:99], v[176:179], v[192:195], v[96:99]
	v_mfma_f32_16x16x32_bf16 v[88:91], v[168:171], v[200:203], v[88:91]
	v_mfma_f32_16x16x32_bf16 v[80:83], v[176:179], v[200:203], v[80:83]
	v_mfma_f32_16x16x32_bf16 v[72:75], v[168:171], v[208:211], v[72:75]
	v_mfma_f32_16x16x32_bf16 v[64:67], v[176:179], v[208:211], v[64:67]
	v_mfma_f32_16x16x32_bf16 v[120:123], v[172:175], v[188:191], v[120:123]
	v_mfma_f32_16x16x32_bf16 v[112:115], v[180:183], v[188:191], v[112:115]
	v_mfma_f32_16x16x32_bf16 v[104:107], v[172:175], v[196:199], v[104:107]
	v_mfma_f32_16x16x32_bf16 v[96:99], v[180:183], v[196:199], v[96:99]
	v_mfma_f32_16x16x32_bf16 v[88:91], v[172:175], v[204:207], v[88:91]
	v_mfma_f32_16x16x32_bf16 v[80:83], v[180:183], v[204:207], v[80:83]
	v_mfma_f32_16x16x32_bf16 v[72:75], v[172:175], v[212:215], v[72:75]
	v_mfma_f32_16x16x32_bf16 v[64:67], v[180:183], v[212:215], v[64:67]
	s_barrier
	s_setprio 0
	s_add_i32 s77, s65, s38
	v_lshl_add_u64 v[144:145], s[30:31], 0, v[132:133]
	s_mov_b32 m0, s77
	ds_read_b128 v[184:187], v150 offset:16384
	ds_read_b128 v[188:191], v150 offset:17408
	ds_read_b128 v[192:195], v150 offset:18432
	ds_read_b128 v[196:199], v150 offset:19456
	ds_read_b128 v[200:203], v150 offset:20480
	ds_read_b128 v[204:207], v150 offset:21504
	ds_read_b128 v[208:211], v150 offset:22528
	ds_read_b128 v[212:215], v150 offset:23552
	global_load_lds_dwordx4 v[144:145], off
	s_add_i32 m0, s77, 0x2000
	s_add_u32 s78, s30, 0x80000
	v_lshl_add_u64 v[216:217], s[30:31], 0, v[128:129]
	s_addc_u32 s79, s31, 0
	s_add_i32 s77, s66, s38
	global_load_lds_dwordx4 v[216:217], off
	v_lshl_add_u64 v[218:219], s[78:79], 0, v[132:133]
	s_mov_b32 m0, s77
	v_lshl_add_u64 v[220:221], s[34:35], 0, v[130:131]
	global_load_lds_dwordx4 v[218:219], off
	v_lshl_add_u64 v[218:219], s[78:79], 0, v[128:129]
	s_add_i32 m0, s77, 0x2000
	s_nop 0
	global_load_lds_dwordx4 v[218:219], off
	v_lshl_add_u64 v[218:219], s[34:35], 0, v[134:135]
	s_mov_b32 m0, s25
	s_nop 0
	global_load_lds_dwordx4 v[218:219], off
	s_mov_b32 m0, s27
	s_nop 0
	global_load_lds_dwordx4 v[220:221], off
	s_setprio 1
	s_waitcnt vmcnt(8) lgkmcnt(0)
	s_barrier
; #define PG8_STAGE(bufoff, gbase, voff) do { _Pragma("unroll") for (int _i = 0; _i < 2; ++_i) \
;         __builtin_amdgcn_global_load_lds((const unsigned*)((const char*)(gbase) + (voff)[_i]), (LAS unsigned*)(lds + (bufoff) + ldsw + _i * 8192), 16, 0, 0); } while (0)
; #define PG8_LDA(dst, b, h) do { _Pragma("unroll") for (int m = 0; m < 4; ++m) _Pragma("unroll") for (int k = 0; k < 2; ++k) dst[m][k] = *(const LAS bf16x8*)(lds + PG8_SA(b, h) + aoff + m * 2048 + k * KOFF); } while (0)
; #define PG8_LDB(dst, b, h) do { _Pragma("unroll") for (int n = 0; n < 2; ++n) _Pragma("unroll") for (int k = 0; k < 2; ++k) dst[n][k] = *(const LAS bf16x8*)(lds + PG8_SB(b, h) + boff + n * 2048 + k * KOFF); } while (0)
; #define PG8_WAIT_V(n) asm volatile("s_waitcnt vmcnt(" #n ")" ::: "memory")
; #define PG8_WAIT_L(n) asm volatile("s_waitcnt lgkmcnt(" #n ")" ::: "memory")
; #define PG8_BAR __builtin_amdgcn_s_barrier()
; #define PG8_SCHED __builtin_amdgcn_sched_barrier(0)
; template <class Epi, bool ALIGN_EPI = true, bool FP8 = false>
; __device__ __forceinline__ void gemm_phase(LAS unsigned char* lds, const Gemm g, const StaticOrder& S, const Epi& E, const int wid) {
;     ...
;             PG8_WAIT_V(8); PG8_WAIT_L(0); PG8_BAR; PG8_MMA(1, 0, At, B0); PG8_MMA(1, 1, At, B1); PG8_BAR; PG8_SCHED;
;             PG8_LDB(B0, 1, 0); PG8_LDB(B1, 1, 1); PG8_SCHED; PG8_LDA(At, 1, 0); PG8_STAGE(PG8_SA(0, 1), a2 + hstep, voffA);
;             PG8_WAIT_V(8); PG8_WAIT_L(0); PG8_BAR; PG8_MMA(0, 0, At, B0); PG8_MMA(0, 1, At, B1); PG8_BAR; PG8_SCHED;
	v_mfma_f32_16x16x32_bf16 v[60:63], v[152:155], v[184:187], v[60:63]
	v_mfma_f32_16x16x32_bf16 v[52:55], v[160:163], v[184:187], v[52:55]
	v_mfma_f32_16x16x32_bf16 v[44:47], v[152:155], v[192:195], v[44:47]
	v_mfma_f32_16x16x32_bf16 v[36:39], v[160:163], v[192:195], v[36:39]
	v_mfma_f32_16x16x32_bf16 v[28:31], v[152:155], v[200:203], v[28:31]
	v_mfma_f32_16x16x32_bf16 v[20:23], v[160:163], v[200:203], v[20:23]
	v_mfma_f32_16x16x32_bf16 v[12:15], v[152:155], v[208:211], v[12:15]
	v_mfma_f32_16x16x32_bf16 v[4:7], v[160:163], v[208:211], v[4:7]
	v_mfma_f32_16x16x32_bf16 v[60:63], v[156:159], v[188:191], v[60:63]
	v_mfma_f32_16x16x32_bf16 v[52:55], v[164:167], v[188:191], v[52:55]
	v_mfma_f32_16x16x32_bf16 v[44:47], v[156:159], v[196:199], v[44:47]
	v_mfma_f32_16x16x32_bf16 v[36:39], v[164:167], v[196:199], v[36:39]
	v_mfma_f32_16x16x32_bf16 v[28:31], v[156:159], v[204:207], v[28:31]
	v_mfma_f32_16x16x32_bf16 v[20:23], v[164:167], v[204:207], v[20:23]
	v_mfma_f32_16x16x32_bf16 v[12:15], v[156:159], v[212:215], v[12:15]
	v_mfma_f32_16x16x32_bf16 v[4:7], v[164:167], v[212:215], v[4:7]
	v_mfma_f32_16x16x32_bf16 v[56:59], v[168:171], v[184:187], v[56:59]
	v_mfma_f32_16x16x32_bf16 v[48:51], v[176:179], v[184:187], v[48:51]
	v_mfma_f32_16x16x32_bf16 v[40:43], v[168:171], v[192:195], v[40:43]
	v_mfma_f32_16x16x32_bf16 v[32:35], v[176:179], v[192:195], v[32:35]
	v_mfma_f32_16x16x32_bf16 v[24:27], v[168:171], v[200:203], v[24:27]
	v_mfma_f32_16x16x32_bf16 v[16:19], v[176:179], v[200:203], v[16:19]
	v_mfma_f32_16x16x32_bf16 v[8:11], v[168:171], v[208:211], v[8:11]
	v_mfma_f32_16x16x32_bf16 v[0:3], v[176:179], v[208:211], v[0:3]
	v_mfma_f32_16x16x32_bf16 v[56:59], v[172:175], v[188:191], v[56:59]
	v_mfma_f32_16x16x32_bf16 v[48:51], v[180:183], v[188:191], v[48:51]
	v_mfma_f32_16x16x32_bf16 v[40:43], v[172:175], v[196:199], v[40:43]
	v_mfma_f32_16x16x32_bf16 v[32:35], v[180:183], v[196:199], v[32:35]
	v_mfma_f32_16x16x32_bf16 v[24:27], v[172:175], v[204:207], v[24:27]
	v_mfma_f32_16x16x32_bf16 v[16:19], v[180:183], v[204:207], v[16:19]
	v_mfma_f32_16x16x32_bf16 v[8:11], v[172:175], v[212:215], v[8:11]
	v_mfma_f32_16x16x32_bf16 v[0:3], v[180:183], v[212:215], v[0:3]
	s_barrier
	s_setprio 0
	s_add_i32 s77, 0, 0x18000
	s_add_i32 s78, 0, 0x1c000
	v_add_u32_e32 v164, s77, v147
	v_add_u32_e32 v180, s78, v147
	ds_read_b128 v[152:155], v164
	ds_read_b128 v[156:159], v164 offset:1024
	ds_read_b128 v[160:163], v164 offset:2048
	ds_read_b128 v[164:167], v164 offset:3072
	ds_read_b128 v[168:171], v180
	ds_read_b128 v[172:175], v180 offset:1024
	ds_read_b128 v[176:179], v180 offset:2048
	ds_read_b128 v[180:183], v180 offset:3072
	s_add_u32 s34, s34, 0x80000
	s_addc_u32 s35, s35, 0
	s_mov_b32 m0, s39
	v_lshl_add_u64 v[222:223], s[34:35], 0, v[134:135]
	ds_read_b128 v[184:187], v150 offset:32768
	ds_read_b128 v[188:191], v150 offset:33792
	ds_read_b128 v[192:195], v150 offset:34816
	ds_read_b128 v[196:199], v150 offset:35840
	ds_read_b128 v[200:203], v150 offset:36864
	ds_read_b128 v[204:207], v150 offset:37888
	ds_read_b128 v[208:211], v150 offset:38912
	ds_read_b128 v[212:215], v150 offset:39936
	global_load_lds_dwordx4 v[222:223], off
	v_lshl_add_u64 v[222:223], s[34:35], 0, v[130:131]
	s_mov_b32 m0, s48
	s_nop 0
	global_load_lds_dwordx4 v[222:223], off
	s_setprio 1
	s_waitcnt vmcnt(8) lgkmcnt(0)
	s_barrier
	v_mfma_f32_16x16x32_bf16 v[124:127], v[152:155], v[184:187], v[124:127]
	v_mfma_f32_16x16x32_bf16 v[116:119], v[160:163], v[184:187], v[116:119]
	v_mfma_f32_16x16x32_bf16 v[108:111], v[152:155], v[192:195], v[108:111]
	v_mfma_f32_16x16x32_bf16 v[100:103], v[160:163], v[192:195], v[100:103]
	v_mfma_f32_16x16x32_bf16 v[92:95], v[152:155], v[200:203], v[92:95]
	v_mfma_f32_16x16x32_bf16 v[84:87], v[160:163], v[200:203], v[84:87]
	v_mfma_f32_16x16x32_bf16 v[76:79], v[152:155], v[208:211], v[76:79]
	v_mfma_f32_16x16x32_bf16 v[68:71], v[160:163], v[208:211], v[68:71]
	v_mfma_f32_16x16x32_bf16 v[124:127], v[156:159], v[188:191], v[124:127]
	v_mfma_f32_16x16x32_bf16 v[116:119], v[164:167], v[188:191], v[116:119]
	v_mfma_f32_16x16x32_bf16 v[108:111], v[156:159], v[196:199], v[108:111]
	v_mfma_f32_16x16x32_bf16 v[100:103], v[164:167], v[196:199], v[100:103]
	v_mfma_f32_16x16x32_bf16 v[92:95], v[156:159], v[204:207], v[92:95]
	v_mfma_f32_16x16x32_bf16 v[84:87], v[164:167], v[204:207], v[84:87]
	v_mfma_f32_16x16x32_bf16 v[76:79], v[156:159], v[212:215], v[76:79]
	v_mfma_f32_16x16x32_bf16 v[68:71], v[164:167], v[212:215], v[68:71]
	v_mfma_f32_16x16x32_bf16 v[120:123], v[168:171], v[184:187], v[120:123]
	v_mfma_f32_16x16x32_bf16 v[112:115], v[176:179], v[184:187], v[112:115]
	v_mfma_f32_16x16x32_bf16 v[104:107], v[168:171], v[192:195], v[104:107]
	v_mfma_f32_16x16x32_bf16 v[96:99], v[176:179], v[192:195], v[96:99]
	v_mfma_f32_16x16x32_bf16 v[88:91], v[168:171], v[200:203], v[88:91]
	v_mfma_f32_16x16x32_bf16 v[80:83], v[176:179], v[200:203], v[80:83]
	v_mfma_f32_16x16x32_bf16 v[72:75], v[168:171], v[208:211], v[72:75]
	v_mfma_f32_16x16x32_bf16 v[64:67], v[176:179], v[208:211], v[64:67]
	v_mfma_f32_16x16x32_bf16 v[120:123], v[172:175], v[188:191], v[120:123]
	v_mfma_f32_16x16x32_bf16 v[112:115], v[180:183], v[188:191], v[112:115]
	v_mfma_f32_16x16x32_bf16 v[104:107], v[172:175], v[196:199], v[104:107]
	v_mfma_f32_16x16x32_bf16 v[96:99], v[180:183], v[196:199], v[96:99]
	v_mfma_f32_16x16x32_bf16 v[88:91], v[172:175], v[204:207], v[88:91]
	v_mfma_f32_16x16x32_bf16 v[80:83], v[180:183], v[204:207], v[80:83]
	v_mfma_f32_16x16x32_bf16 v[72:75], v[172:175], v[212:215], v[72:75]
	v_mfma_f32_16x16x32_bf16 v[64:67], v[180:183], v[212:215], v[64:67]
	s_barrier
; #define PG8_STAGE(bufoff, gbase, voff) do { _Pragma("unroll") for (int _i = 0; _i < 2; ++_i) \
;         __builtin_amdgcn_global_load_lds((const unsigned*)((const char*)(gbase) + (voff)[_i]), (LAS unsigned*)(lds + (bufoff) + ldsw + _i * 8192), 16, 0, 0); } while (0)
; #define PG8_LDA(dst, b, h) do { _Pragma("unroll") for (int m = 0; m < 4; ++m) _Pragma("unroll") for (int k = 0; k < 2; ++k) dst[m][k] = *(const LAS bf16x8*)(lds + PG8_SA(b, h) + aoff + m * 2048 + k * KOFF); } while (0)
; #define PG8_WAIT_V(n) asm volatile("s_waitcnt vmcnt(" #n ")" ::: "memory")
; #define PG8_WAIT_L(n) asm volatile("s_waitcnt lgkmcnt(" #n ")" ::: "memory")
; #define PG8_BAR __builtin_amdgcn_s_barrier()
; #define PG8_SCHED __builtin_amdgcn_sched_barrier(0)
; template <class Epi, bool ALIGN_EPI = true, bool FP8 = false>
; __device__ __forceinline__ void gemm_phase(LAS unsigned char* lds, const Gemm g, const StaticOrder& S, const Epi& E, const int wid) {
;     ...
;             PG8_LDA(At, 1, 1); PG8_STAGE(PG8_SB(1, 0), b3, voffB); PG8_STAGE(PG8_SB(1, 1), b3 + hstep, voffB); PG8_STAGE(PG8_SA(1, 0), a3, voffA);
;             PG8_WAIT_V(8); PG8_WAIT_L(0); PG8_BAR; PG8_MMA(1, 0, At, B0); PG8_MMA(1, 1, At, B1); PG8_BAR; PG8_SCHED;
;         }
;         if constexpr (ALIGN_EPI) { if (wr == 0) PG8_BAR; }
	s_setprio 0
	s_add_i32 s34, s77, s38
	v_lshl_add_u64 v[144:145], v[144:145], 0, s[14:15]
	s_mov_b32 m0, s34
	ds_read_b128 v[184:187], v150 offset:49152
	ds_read_b128 v[188:191], v150 offset:50176
	ds_read_b128 v[192:195], v150 offset:51200
	ds_read_b128 v[196:199], v150 offset:52224
	ds_read_b128 v[200:203], v150 offset:53248
	ds_read_b128 v[204:207], v150 offset:54272
	ds_read_b128 v[208:211], v150 offset:55296
	ds_read_b128 v[212:215], v150 offset:56320
	global_load_lds_dwordx4 v[144:145], off
	s_add_i32 m0, s34, 0x2000
	s_add_u32 s30, s30, 0x80080
	v_lshl_add_u64 v[144:145], v[216:217], 0, s[14:15]
	s_addc_u32 s31, s31, 0
	s_add_i32 s34, s78, s38
	global_load_lds_dwordx4 v[144:145], off
	v_lshl_add_u64 v[144:145], s[30:31], 0, v[132:133]
	s_mov_b32 m0, s34
	s_nop 0
	global_load_lds_dwordx4 v[144:145], off
	v_lshl_add_u64 v[144:145], s[30:31], 0, v[128:129]
	s_add_i32 m0, s34, 0x2000
	s_nop 0
	global_load_lds_dwordx4 v[144:145], off
	v_lshl_add_u64 v[144:145], v[218:219], 0, s[14:15]
	s_mov_b32 m0, s53
	s_nop 0
	global_load_lds_dwordx4 v[144:145], off
	v_lshl_add_u64 v[144:145], v[220:221], 0, s[14:15]
	s_mov_b32 m0, s55
	s_nop 0
	global_load_lds_dwordx4 v[144:145], off
	s_setprio 1
	s_waitcnt vmcnt(8) lgkmcnt(0)
	s_barrier
	v_mfma_f32_16x16x32_bf16 v[60:63], v[152:155], v[184:187], v[60:63]
	v_mfma_f32_16x16x32_bf16 v[52:55], v[160:163], v[184:187], v[52:55]
	v_mfma_f32_16x16x32_bf16 v[44:47], v[152:155], v[192:195], v[44:47]
	v_mfma_f32_16x16x32_bf16 v[36:39], v[160:163], v[192:195], v[36:39]
	v_mfma_f32_16x16x32_bf16 v[28:31], v[152:155], v[200:203], v[28:31]
	v_mfma_f32_16x16x32_bf16 v[20:23], v[160:163], v[200:203], v[20:23]
	v_mfma_f32_16x16x32_bf16 v[12:15], v[152:155], v[208:211], v[12:15]
	v_mfma_f32_16x16x32_bf16 v[4:7], v[160:163], v[208:211], v[4:7]
	v_mfma_f32_16x16x32_bf16 v[60:63], v[156:159], v[188:191], v[60:63]
	v_mfma_f32_16x16x32_bf16 v[52:55], v[164:167], v[188:191], v[52:55]
	v_mfma_f32_16x16x32_bf16 v[44:47], v[156:159], v[196:199], v[44:47]
	v_mfma_f32_16x16x32_bf16 v[36:39], v[164:167], v[196:199], v[36:39]
	v_mfma_f32_16x16x32_bf16 v[28:31], v[156:159], v[204:207], v[28:31]
	v_mfma_f32_16x16x32_bf16 v[20:23], v[164:167], v[204:207], v[20:23]
	v_mfma_f32_16x16x32_bf16 v[12:15], v[156:159], v[212:215], v[12:15]
	v_mfma_f32_16x16x32_bf16 v[4:7], v[164:167], v[212:215], v[4:7]
	v_mfma_f32_16x16x32_bf16 v[56:59], v[168:171], v[184:187], v[56:59]
	v_mfma_f32_16x16x32_bf16 v[48:51], v[176:179], v[184:187], v[48:51]
	v_mfma_f32_16x16x32_bf16 v[40:43], v[168:171], v[192:195], v[40:43]
	v_mfma_f32_16x16x32_bf16 v[32:35], v[176:179], v[192:195], v[32:35]
	v_mfma_f32_16x16x32_bf16 v[24:27], v[168:171], v[200:203], v[24:27]
	v_mfma_f32_16x16x32_bf16 v[16:19], v[176:179], v[200:203], v[16:19]
	v_mfma_f32_16x16x32_bf16 v[8:11], v[168:171], v[208:211], v[8:11]
	v_mfma_f32_16x16x32_bf16 v[0:3], v[176:179], v[208:211], v[0:3]
	v_mfma_f32_16x16x32_bf16 v[56:59], v[172:175], v[188:191], v[56:59]
	v_mfma_f32_16x16x32_bf16 v[48:51], v[180:183], v[188:191], v[48:51]
	v_mfma_f32_16x16x32_bf16 v[40:43], v[172:175], v[196:199], v[40:43]
	v_mfma_f32_16x16x32_bf16 v[32:35], v[180:183], v[196:199], v[32:35]
	v_mfma_f32_16x16x32_bf16 v[24:27], v[172:175], v[204:207], v[24:27]
	v_mfma_f32_16x16x32_bf16 v[16:19], v[180:183], v[204:207], v[16:19]
	v_mfma_f32_16x16x32_bf16 v[8:11], v[172:175], v[212:215], v[8:11]
	v_mfma_f32_16x16x32_bf16 v[0:3], v[180:183], v[212:215], v[0:3]
	s_barrier
	s_setprio 0
	s_add_u32 s28, s28, 0x100
	s_addc_u32 s29, s29, 0
	s_add_u32 s52, s52, 0x100
	s_addc_u32 s75, s75, 0
	s_cmp_ge_u32 s76, s54
	s_mov_b32 s30, s76
	s_cbranch_scc0 .LBB0_2452
	s_and_b64 vcc, exec, s[12:13]
	s_cbranch_vccz .LBB0_2455

; #define PG8_STAGE(bufoff, gbase, voff) do { _Pragma("unroll") for (int _i = 0; _i < 2; ++_i) \
;         __builtin_amdgcn_global_load_lds((const unsigned*)((const char*)(gbase) + (voff)[_i]), (LAS unsigned*)(lds + (bufoff) + ldsw + _i * 8192), 16, 0, 0); } while (0)
; #define PG8_LDA(dst, b, h) do { _Pragma("unroll") for (int m = 0; m < 4; ++m) _Pragma("unroll") for (int k = 0; k < 2; ++k) dst[m][k] = *(const LAS bf16x8*)(lds + PG8_SA(b, h) + aoff + m * 2048 + k * KOFF); } while (0)
; #define PG8_LDB(dst, b, h) do { _Pragma("unroll") for (int n = 0; n < 2; ++n) _Pragma("unroll") for (int k = 0; k < 2; ++k) dst[n][k] = *(const LAS bf16x8*)(lds + PG8_SB(b, h) + boff + n * 2048 + k * KOFF); } while (0)
; #define PG8_WAIT_V(n) asm volatile("s_waitcnt vmcnt(" #n ")" ::: "memory")
; #define PG8_WAIT_L(n) asm volatile("s_waitcnt lgkmcnt(" #n ")" ::: "memory")
; #define PG8_BAR __builtin_amdgcn_s_barrier()
; #define PG8_SCHED __builtin_amdgcn_sched_barrier(0)
; template <class Epi, bool ALIGN_EPI = true, bool FP8 = false>
; __device__ __forceinline__ void gemm_phase(LAS unsigned char* lds, const Gemm g, const StaticOrder& S, const Epi& E, const int wid) {
;     ...
;             const char* a1 = cA + (size_t)(t + 1) * kstep;
;             const char* a2 = last ? nA : cA + (size_t)(t + 2) * kstep; const char* b2 = last ? nB : cB + (size_t)(t + 2) * kstep;
;             const char* a3 = a2 + kstep; const char* b3 = b2 + kstep;
;             PG8_LDB(B0, 0, 0); PG8_LDB(B1, 0, 1); PG8_SCHED; PG8_LDA(At, 0, 0); PG8_STAGE(PG8_SA(1, 1), a1 + hstep, voffA);
;             PG8_WAIT_V(8); PG8_WAIT_L(0); PG8_BAR; PG8_MMA(0, 0, At, B0); PG8_MMA(0, 1, At, B1); PG8_BAR; PG8_SCHED;
;             PG8_LDA(At, 0, 1); PG8_STAGE(PG8_SB(0, 0), b2, voffB); PG8_STAGE(PG8_SB(0, 1), b2 + hstep, voffB); PG8_STAGE(PG8_SA(0, 0), a2, voffA);
;             PG8_WAIT_V(8); PG8_WAIT_L(0); PG8_BAR; PG8_MMA(1, 0, At, B0); PG8_MMA(1, 1, At, B1); PG8_BAR; PG8_SCHED;
.LBB0_2536:
	ds_read_b128 v[152:155], v188
	ds_read_b128 v[156:159], v188 offset:1024
	ds_read_b128 v[144:147], v188 offset:2048
	ds_read_b128 v[148:151], v188 offset:3072
	ds_read_b128 v[136:139], v189
	ds_read_b128 v[140:143], v189 offset:1024
	ds_read_b128 v[128:131], v189 offset:2048
	ds_read_b128 v[132:135], v189 offset:3072
	s_add_i32 s42, s26, 2
	s_add_u32 s27, s24, 0xfff50080
	s_addc_u32 s28, s25, -1
	s_cmp_eq_u32 s81, s26
	s_cselect_b32 s26, s20, s82
	s_cselect_b32 s29, s7, s28
	s_cselect_b32 s28, s6, s27
	s_cselect_b32 s27, s21, s83
	v_lshl_add_u64 v[216:217], s[24:25], 0, v[172:173]
	s_add_i32 m0, s34, 0xc000
	ds_read_b128 v[178:181], v190
	ds_read_b128 v[182:185], v190 offset:1024
	ds_read_b128 v[192:195], v190 offset:2048
	ds_read_b128 v[196:199], v190 offset:3072
	ds_read_b128 v[200:203], v190 offset:4096
	ds_read_b128 v[204:207], v190 offset:5120
	ds_read_b128 v[208:211], v190 offset:6144
	ds_read_b128 v[212:215], v190 offset:7168
	global_load_lds_dwordx4 v[216:217], off
	v_lshl_add_u64 v[216:217], s[24:25], 0, v[174:175]
	s_add_i32 m0, s34, 0xe000
	s_nop 0
	global_load_lds_dwordx4 v[216:217], off
	s_setprio 1
	s_waitcnt vmcnt(8) lgkmcnt(0)
	s_barrier
	v_mfma_f32_16x16x128_f8f6f4 v[120:123], v[152:159], v[178:185], v[120:123]
	v_mfma_f32_16x16x128_f8f6f4 v[124:127], v[144:151], v[178:185], v[124:127]
	v_mfma_f32_16x16x128_f8f6f4 v[112:115], v[152:159], v[192:199], v[112:115]
	v_mfma_f32_16x16x128_f8f6f4 v[116:119], v[144:151], v[192:199], v[116:119]
	v_mfma_f32_16x16x128_f8f6f4 v[96:99], v[152:159], v[200:207], v[96:99]
	v_mfma_f32_16x16x128_f8f6f4 v[100:103], v[144:151], v[200:207], v[100:103]
	v_mfma_f32_16x16x128_f8f6f4 v[80:83], v[152:159], v[208:215], v[80:83]
	v_mfma_f32_16x16x128_f8f6f4 v[84:87], v[144:151], v[208:215], v[84:87]
	v_mfma_f32_16x16x128_f8f6f4 v[104:107], v[136:143], v[178:185], v[104:107]
	v_mfma_f32_16x16x128_f8f6f4 v[108:111], v[128:135], v[178:185], v[108:111]
	v_mfma_f32_16x16x128_f8f6f4 v[88:91], v[136:143], v[192:199], v[88:91]
	v_mfma_f32_16x16x128_f8f6f4 v[92:95], v[128:135], v[192:199], v[92:95]
	v_mfma_f32_16x16x128_f8f6f4 v[72:75], v[136:143], v[200:207], v[72:75]
	v_mfma_f32_16x16x128_f8f6f4 v[76:79], v[128:135], v[200:207], v[76:79]
	v_mfma_f32_16x16x128_f8f6f4 v[64:67], v[136:143], v[208:215], v[64:67]
	v_mfma_f32_16x16x128_f8f6f4 v[68:71], v[128:135], v[208:215], v[68:71]
	s_barrier
	s_setprio 0
	s_add_i32 s43, s64, s31
	v_lshl_add_u64 v[178:179], s[26:27], 0, v[162:163]
	s_mov_b32 m0, s43
	ds_read_b128 v[192:195], v190 offset:16384
	ds_read_b128 v[196:199], v190 offset:17408
	ds_read_b128 v[200:203], v190 offset:18432
	ds_read_b128 v[204:207], v190 offset:19456
	ds_read_b128 v[208:211], v190 offset:20480
	ds_read_b128 v[212:215], v190 offset:21504
	ds_read_b128 v[216:219], v190 offset:22528
	ds_read_b128 v[220:223], v190 offset:23552
	global_load_lds_dwordx4 v[178:179], off
	s_add_i32 m0, s43, 0x2000
	s_add_u32 s84, s26, 0xb0000
	v_lshl_add_u64 v[180:181], s[26:27], 0, v[166:167]
	s_addc_u32 s85, s27, 0
	s_add_i32 s43, s65, s31
	global_load_lds_dwordx4 v[180:181], off
	v_lshl_add_u64 v[182:183], s[84:85], 0, v[162:163]
	s_mov_b32 m0, s43
	v_lshl_add_u64 v[184:185], s[28:29], 0, v[164:165]
	global_load_lds_dwordx4 v[182:183], off
	v_lshl_add_u64 v[182:183], s[84:85], 0, v[166:167]
	s_add_i32 m0, s43, 0x2000
	s_nop 0
	global_load_lds_dwordx4 v[182:183], off
	v_lshl_add_u64 v[182:183], s[28:29], 0, v[160:161]
	s_mov_b32 m0, s34
	s_nop 0
	global_load_lds_dwordx4 v[182:183], off
	s_mov_b32 m0, s35
	s_nop 0
	global_load_lds_dwordx4 v[184:185], off
	s_setprio 1
	s_waitcnt vmcnt(8) lgkmcnt(0)
	s_barrier
	v_mfma_f32_16x16x128_f8f6f4 v[56:59], v[152:159], v[192:199], v[56:59]
	v_mfma_f32_16x16x128_f8f6f4 v[60:63], v[144:151], v[192:199], v[60:63]
	v_mfma_f32_16x16x128_f8f6f4 v[48:51], v[152:159], v[200:207], v[48:51]
	v_mfma_f32_16x16x128_f8f6f4 v[52:55], v[144:151], v[200:207], v[52:55]
	v_mfma_f32_16x16x128_f8f6f4 v[32:35], v[152:159], v[208:215], v[32:35]
	v_mfma_f32_16x16x128_f8f6f4 v[224:227], v[144:151], v[208:215], v[36:39]
	v_mfma_f32_16x16x128_f8f6f4 v[228:231], v[152:159], v[216:223], v[16:19]
	v_mfma_f32_16x16x128_f8f6f4 v[232:235], v[144:151], v[216:223], v[20:23]
	v_mfma_f32_16x16x128_f8f6f4 v[44:47], v[128:135], v[192:199], v[44:47]
	v_mfma_f32_16x16x128_f8f6f4 v[236:239], v[136:143], v[192:199], v[40:43]
	v_mfma_f32_16x16x128_f8f6f4 v[240:243], v[136:143], v[200:207], v[24:27]
	v_mfma_f32_16x16x128_f8f6f4 v[200:203], v[128:135], v[200:207], v[28:31]
	v_mfma_f32_16x16x128_f8f6f4 v[204:207], v[136:143], v[208:215], v[8:11]
	v_mfma_f32_16x16x128_f8f6f4 v[208:211], v[128:135], v[208:215], v[12:15]
	v_mfma_f32_16x16x128_f8f6f4 v[212:215], v[136:143], v[216:223], v[0:3]
	v_mfma_f32_16x16x128_f8f6f4 v[216:219], v[128:135], v[216:223], v[4:7]
	s_barrier
; #define PG8_STAGE(bufoff, gbase, voff) do { _Pragma("unroll") for (int _i = 0; _i < 2; ++_i) \
;         __builtin_amdgcn_global_load_lds((const unsigned*)((const char*)(gbase) + (voff)[_i]), (LAS unsigned*)(lds + (bufoff) + ldsw + _i * 8192), 16, 0, 0); } while (0)
; #define PG8_LDA(dst, b, h) do { _Pragma("unroll") for (int m = 0; m < 4; ++m) _Pragma("unroll") for (int k = 0; k < 2; ++k) dst[m][k] = *(const LAS bf16x8*)(lds + PG8_SA(b, h) + aoff + m * 2048 + k * KOFF); } while (0)
; #define PG8_LDB(dst, b, h) do { _Pragma("unroll") for (int n = 0; n < 2; ++n) _Pragma("unroll") for (int k = 0; k < 2; ++k) dst[n][k] = *(const LAS bf16x8*)(lds + PG8_SB(b, h) + boff + n * 2048 + k * KOFF); } while (0)
; #define PG8_WAIT_V(n) asm volatile("s_waitcnt vmcnt(" #n ")" ::: "memory")
; #define PG8_WAIT_L(n) asm volatile("s_waitcnt lgkmcnt(" #n ")" ::: "memory")
; #define PG8_BAR __builtin_amdgcn_s_barrier()
; #define PG8_SCHED __builtin_amdgcn_sched_barrier(0)
; template <class Epi, bool ALIGN_EPI = true, bool FP8 = false>
; __device__ __forceinline__ void gemm_phase(LAS unsigned char* lds, const Gemm g, const StaticOrder& S, const Epi& E, const int wid) {
;     ...
;             PG8_LDB(B0, 1, 0); PG8_LDB(B1, 1, 1); PG8_SCHED; PG8_LDA(At, 1, 0); PG8_STAGE(PG8_SA(0, 1), a2 + hstep, voffA);
;             PG8_WAIT_V(8); PG8_WAIT_L(0); PG8_BAR; PG8_MMA(0, 0, At, B0); PG8_MMA(0, 1, At, B1); PG8_BAR; PG8_SCHED;
;             PG8_LDA(At, 1, 1); PG8_STAGE(PG8_SB(1, 0), b3, voffB); PG8_STAGE(PG8_SB(1, 1), b3 + hstep, voffB); PG8_STAGE(PG8_SA(1, 0), a3, voffA);
;             PG8_WAIT_V(8); PG8_WAIT_L(0); PG8_BAR; PG8_MMA(1, 0, At, B0); PG8_MMA(1, 1, At, B1); PG8_BAR; PG8_SCHED;
;         }
;         if constexpr (ALIGN_EPI) { if (wr == 0) PG8_BAR; }
	s_setprio 0
	s_add_i32 s43, 0, 0x18000
	s_add_i32 s54, 0, 0x1c000
	s_nop 0
	v_add_u32_e32 v12, s43, v187
	v_add_u32_e32 v16, s54, v187
	ds_read_b128 v[0:3], v12
	ds_read_b128 v[4:7], v12 offset:1024
	ds_read_b128 v[8:11], v12 offset:2048
	ds_read_b128 v[12:15], v12 offset:3072
	ds_read_b128 v[128:131], v16
	ds_read_b128 v[132:135], v16 offset:1024
	ds_read_b128 v[136:139], v16 offset:2048
	ds_read_b128 v[140:143], v16 offset:3072
	s_add_u32 s28, s28, 0xb0000
	s_addc_u32 s29, s29, 0
	s_mov_b32 m0, s36
	v_lshl_add_u64 v[152:153], s[28:29], 0, v[160:161]
	ds_read_b128 v[16:19], v190 offset:32768
	ds_read_b128 v[20:23], v190 offset:33792
	ds_read_b128 v[24:27], v190 offset:34816
	ds_read_b128 v[28:31], v190 offset:35840
	ds_read_b128 v[36:39], v190 offset:36864
	ds_read_b128 v[40:43], v190 offset:37888
	ds_read_b128 v[144:147], v190 offset:38912
	ds_read_b128 v[148:151], v190 offset:39936
	global_load_lds_dwordx4 v[152:153], off
	v_lshl_add_u64 v[152:153], s[28:29], 0, v[164:165]
	s_mov_b32 m0, s37
	s_nop 0
	global_load_lds_dwordx4 v[152:153], off
	s_setprio 1
	s_waitcnt vmcnt(8) lgkmcnt(0)
	s_barrier
	v_mfma_f32_16x16x128_f8f6f4 v[120:123], v[0:7], v[16:23], v[120:123]
	v_mfma_f32_16x16x128_f8f6f4 v[124:127], v[8:15], v[16:23], v[124:127]
	v_mfma_f32_16x16x128_f8f6f4 v[112:115], v[0:7], v[24:31], v[112:115]
	v_mfma_f32_16x16x128_f8f6f4 v[116:119], v[8:15], v[24:31], v[116:119]
	v_mfma_f32_16x16x128_f8f6f4 v[96:99], v[0:7], v[36:43], v[96:99]
	v_mfma_f32_16x16x128_f8f6f4 v[100:103], v[8:15], v[36:43], v[100:103]
	v_mfma_f32_16x16x128_f8f6f4 v[80:83], v[0:7], v[144:151], v[80:83]
	v_mfma_f32_16x16x128_f8f6f4 v[84:87], v[8:15], v[144:151], v[84:87]
	v_mfma_f32_16x16x128_f8f6f4 v[104:107], v[128:135], v[16:23], v[104:107]
	v_mfma_f32_16x16x128_f8f6f4 v[108:111], v[136:143], v[16:23], v[108:111]
	v_mfma_f32_16x16x128_f8f6f4 v[88:91], v[128:135], v[24:31], v[88:91]
	v_mfma_f32_16x16x128_f8f6f4 v[92:95], v[136:143], v[24:31], v[92:95]
	v_mfma_f32_16x16x128_f8f6f4 v[72:75], v[128:135], v[36:43], v[72:75]
	v_mfma_f32_16x16x128_f8f6f4 v[76:79], v[136:143], v[36:43], v[76:79]
	v_mfma_f32_16x16x128_f8f6f4 v[64:67], v[128:135], v[144:151], v[64:67]
	v_mfma_f32_16x16x128_f8f6f4 v[68:71], v[136:143], v[144:151], v[68:71]
	s_barrier
	s_setprio 0
	s_add_i32 s28, s43, s31
	v_lshl_add_u64 v[16:17], v[178:179], 0, s[14:15]
	s_mov_b32 m0, s28
	ds_read_b128 v[24:27], v190 offset:49152
	ds_read_b128 v[28:31], v190 offset:50176
	ds_read_b128 v[144:147], v190 offset:51200
	ds_read_b128 v[148:151], v190 offset:52224
	ds_read_b128 v[152:155], v190 offset:53248
	ds_read_b128 v[156:159], v190 offset:54272
	ds_read_b128 v[192:195], v190 offset:55296
	ds_read_b128 v[196:199], v190 offset:56320
	global_load_lds_dwordx4 v[16:17], off
	s_add_i32 m0, s28, 0x2000
	s_add_u32 s26, s26, 0xb0080
	v_lshl_add_u64 v[16:17], v[180:181], 0, s[14:15]
	s_addc_u32 s27, s27, 0
	s_add_i32 s28, s54, s31
	global_load_lds_dwordx4 v[16:17], off
	v_lshl_add_u64 v[16:17], s[26:27], 0, v[162:163]
	s_mov_b32 m0, s28
	s_nop 0
	global_load_lds_dwordx4 v[16:17], off
	v_lshl_add_u64 v[16:17], s[26:27], 0, v[166:167]
	s_add_i32 m0, s28, 0x2000
	s_nop 0
	global_load_lds_dwordx4 v[16:17], off
	v_lshl_add_u64 v[16:17], v[182:183], 0, s[14:15]
	s_mov_b32 m0, s52
	s_nop 0
	global_load_lds_dwordx4 v[16:17], off
	v_lshl_add_u64 v[16:17], v[184:185], 0, s[14:15]
	s_mov_b32 m0, s53
	s_nop 0
	global_load_lds_dwordx4 v[16:17], off
	s_setprio 1
	s_waitcnt vmcnt(8) lgkmcnt(0)
	s_barrier
	v_mfma_f32_16x16x128_f8f6f4 v[56:59], v[0:7], v[24:31], v[56:59]
	v_mfma_f32_16x16x128_f8f6f4 v[60:63], v[8:15], v[24:31], v[60:63]
	v_mfma_f32_16x16x128_f8f6f4 v[48:51], v[0:7], v[144:151], v[48:51]
	v_mfma_f32_16x16x128_f8f6f4 v[52:55], v[8:15], v[144:151], v[52:55]
	v_mfma_f32_16x16x128_f8f6f4 v[32:35], v[0:7], v[152:159], v[32:35]
	v_mfma_f32_16x16x128_f8f6f4 v[36:39], v[8:15], v[152:159], v[224:227]
	v_mfma_f32_16x16x128_f8f6f4 v[16:19], v[0:7], v[192:199], v[228:231]
	v_mfma_f32_16x16x128_f8f6f4 v[20:23], v[8:15], v[192:199], v[232:235]
	v_mfma_f32_16x16x128_f8f6f4 v[40:43], v[128:135], v[24:31], v[236:239]
	v_mfma_f32_16x16x128_f8f6f4 v[44:47], v[136:143], v[24:31], v[44:47]
	v_mfma_f32_16x16x128_f8f6f4 v[24:27], v[128:135], v[144:151], v[240:243]
	v_mfma_f32_16x16x128_f8f6f4 v[28:31], v[136:143], v[144:151], v[200:203]
	v_mfma_f32_16x16x128_f8f6f4 v[8:11], v[128:135], v[152:159], v[204:207]
	v_mfma_f32_16x16x128_f8f6f4 v[12:15], v[136:143], v[152:159], v[208:211]
	v_mfma_f32_16x16x128_f8f6f4 v[0:3], v[128:135], v[192:199], v[212:215]
	v_mfma_f32_16x16x128_f8f6f4 v[4:7], v[136:143], v[192:199], v[216:219]
	s_barrier
	s_setprio 0
	s_add_u32 s24, s24, 0x100
	s_addc_u32 s25, s25, 0
	s_add_u32 s82, s82, 0x100
	s_addc_u32 s83, s83, 0
	s_cmp_ge_u32 s42, s80
	s_mov_b32 s26, s42
	s_cbranch_scc0 .LBB0_2536
	s_and_b64 vcc, exec, s[16:17]
	s_cbranch_vccz .LBB0_2539
	s_barrier
